# FFN-up epilogue: 256 ds_bpermute row shuffles per wave replaced by DPP row_ror moves (no LDS crossbar, lgkmcnt waits dropped)
# speedup vs baseline: 1.0182x; 1.0168x over previous
;     __device__ __forceinline__ void operator()(const f32x4 (&acc)[2][2][4][2], const Unit& u, int wr, int wc, int fr_, int fq_) const {
;     ...
;         asm volatile("s_waitcnt lgkmcnt(0)" ::: "memory"); __builtin_amdgcn_s_barrier(); asm volatile("" ::: "memory");
;         const int chg = u.pn * 128 + cl;
; #pragma unroll
;         for (int n = 0; n < 2; ++n) {
;             f32x4 w0[2], w1[2], w2[2], bv[2];
; #pragma unroll
;             for (int bj = 0; bj < 2; ++bj) { const int wcol = bj * 2816 + chg + 4 * n; w0[bj] = *(const f32x4*)(cw + wcol); w1[bj] = *(const f32x4*)(cw + 5632 + wcol); w2[bj] = *(const f32x4*)(cw + 2 * 5632 + wcol); bv[bj] = *(const f32x4*)(cb + wcol); }
; #pragma unroll
;             for (int ai = 0; ai < 2; ++ai) {
;                 const int sp = (wr == 1) ? ((ai * 2 + 0) * 2 + 1) : (ai == 1 ? ((0 * 2 + 1) * 2 + 1) : -1);
;                 const int sn = (wr == 0) ? ((ai * 2 + 1) * 2 + 0) : (ai == 0 ? ((1 * 2 + 0) * 2 + 0) : -1);
; #pragma unroll
;                 for (int m = 0; m < 4; ++m) { f32x4 cv[2];
; #pragma unroll
;                     for (int bj = 0; bj < 2; ++bj) {
;                         const f32x4 cur = acc[ai][bj][m][n];
;                         const f32x4 su = (fr == 15 && m > 0) ? acc[ai][bj][m > 0 ? m - 1 : 0][n] : cur;
;                         const f32x4 sd = (fr == 0 && m < 3) ? acc[ai][bj][m < 3 ? m + 1 : 3][n] : cur;
;                         f32x4 up, dn;
; #pragma unroll
;                         for (int e = 0; e < 4; ++e) { up[e] = __shfl(su[e], srcu); dn[e] = __shfl(sd[e], srcd); }
;                         if (m == 0) { f32x4 pv = (f32x4){0.f, 0.f, 0.f, 0.f}; if (sp >= 0) pv = *(const PG8_LAS f32x4*)(xch + sp * 256 + 128 * bj + cl + 4 * n); if (fr == 0) up = pv; }
;                         if (m == 3) { f32x4 nv = (f32x4){0.f, 0.f, 0.f, 0.f}; if (sn >= 0) nv = *(const PG8_LAS f32x4*)(xch + sn * 256 + 128 * bj + cl + 4 * n); if (fr == 15) dn = nv; }
;                         cv[bj] = bv[bj] + w0[bj] * up + w1[bj] * cur + w2[bj] * dn; }
;                     u32x2 hw; hw.x = pk2(cv[0][0] * sigmoidf_(cv[0][0]) * cv[1][0], cv[0][1] * sigmoidf_(cv[0][1]) * cv[1][1]); hw.y = pk2(cv[0][2] * sigmoidf_(cv[0][2]) * cv[1][2], cv[0][3] * sigmoidf_(cv[0][3]) * cv[1][3]);
;                     *(u32x2*)(H + (size_t)(u.pm * BM + ai * HALF + wr * 64 + m * 16 + fr) * 2816 + chg + 4 * n) = hw;
.LBB0_1820:
	s_or_b64 exec, exec, s[8:9]
	v_lshl_add_u32 v178, s14, 7, v160
	v_ashrrev_i32_e32 v179, 31, v178
	v_lshlrev_b64 v[128:129], 2, v[178:179]
	v_lshl_add_u64 v[180:181], s[22:23], 0, v[128:129]
	v_lshl_add_u64 v[130:131], s[28:29], 0, v[128:129]
	v_lshl_add_u64 v[132:133], s[30:31], 0, v[128:129]
	v_lshl_add_u64 v[182:183], s[24:25], 0, v[128:129]
	v_add_u32_e32 v128, 0xb00, v178
	v_ashrrev_i32_e32 v129, 31, v128
	v_lshlrev_b64 v[144:145], 2, v[128:129]
	s_waitcnt lgkmcnt(0)
	s_barrier
	v_lshl_add_u64 v[128:129], s[22:23], 0, v[144:145]
	global_load_dwordx4 v[152:155], v[180:181], off
	global_load_dwordx4 v[148:151], v[130:131], off
	global_load_dwordx4 v[140:143], v[132:133], off
	global_load_dwordx4 v[156:159], v[182:183], off
	v_lshl_add_u64 v[130:131], s[28:29], 0, v[144:145]
	global_load_dwordx4 v[136:139], v[128:129], off
	global_load_dwordx4 v[132:135], v[130:131], off
	v_lshl_add_u64 v[128:129], s[30:31], 0, v[144:145]
	v_lshl_add_u64 v[144:145], s[24:25], 0, v[144:145]
	global_load_dwordx4 v[128:131], v[128:129], off
	v_add_u32_e32 v161, -1, v233
	global_load_dwordx4 v[144:147], v[144:145], off
	v_lshl_add_u32 v162, v162, 4, v233
	v_and_b32_e32 v161, 15, v161
	v_add_u32_e32 v163, 1, v233
	v_and_b32_e32 v162, 48, v162
	v_and_b32_e32 v163, 15, v163
	v_or3_b32 v161, v162, v161, v211
	v_lshlrev_b32_e32 v215, 2, v161
	v_or3_b32 v161, v162, v163, v211
	v_cmp_eq_u32_e64 s[10:11], 0, v233
	v_lshlrev_b32_e32 v222, 2, v161
	v_lshl_add_u32 v231, v160, 2, s66
	v_cndmask_b32_e64 v160, v127, v123, s[10:11]
	v_cndmask_b32_e64 v161, v126, v122, s[10:11]
	v_cndmask_b32_e64 v162, v125, v121, s[10:11]
	v_cndmask_b32_e64 v163, v124, v120, s[10:11]
	v_mov_b32_dpp v234, v124 row_ror:1 row_mask:0xf bank_mask:0xf
	s_nop 0
	v_mov_b32_dpp v186, v163 row_ror:15 row_mask:0xf bank_mask:0xf
	v_mov_b32_dpp v236, v125 row_ror:1 row_mask:0xf bank_mask:0xf
	v_mov_b32_dpp v187, v162 row_ror:15 row_mask:0xf bank_mask:0xf
	v_mov_b32_dpp v235, v126 row_ror:1 row_mask:0xf bank_mask:0xf
	v_mov_b32_dpp v192, v161 row_ror:15 row_mask:0xf bank_mask:0xf
	v_mov_b32_dpp v237, v127 row_ror:1 row_mask:0xf bank_mask:0xf
	v_mov_b32_dpp v193, v160 row_ror:15 row_mask:0xf bank_mask:0xf
	v_cndmask_b32_e64 v161, 0, 1, s[16:17]
	v_mov_b32_e32 v160, 0
	v_cmp_ne_u32_e64 s[8:9], 1, v161
	s_andn2_b64 vcc, exec, s[16:17]
	v_mov_b32_e32 v164, 0
	v_mov_b32_e32 v165, 0
	v_mov_b32_e32 v166, 0
	v_mov_b32_e32 v167, 0
	s_cbranch_vccnz .LBB0_1822
	ds_read_b128 v[164:167], v231
.LBB0_1822:
	v_cndmask_b32_e64 v161, v119, v115, s[10:11]
	v_cndmask_b32_e64 v162, v118, v114, s[10:11]
	v_cndmask_b32_e64 v163, v117, v113, s[10:11]
	v_cndmask_b32_e64 v184, v116, v112, s[10:11]
	v_mov_b32_dpp v238, v116 row_ror:1 row_mask:0xf bank_mask:0xf
	s_nop 0
	v_mov_b32_dpp v184, v184 row_ror:15 row_mask:0xf bank_mask:0xf
	v_mov_b32_dpp v240, v117 row_ror:1 row_mask:0xf bank_mask:0xf
	v_mov_b32_dpp v185, v163 row_ror:15 row_mask:0xf bank_mask:0xf
	v_mov_b32_dpp v239, v118 row_ror:1 row_mask:0xf bank_mask:0xf
	v_mov_b32_dpp v194, v162 row_ror:15 row_mask:0xf bank_mask:0xf
	v_mov_b32_dpp v241, v119 row_ror:1 row_mask:0xf bank_mask:0xf
	v_mov_b32_dpp v195, v161 row_ror:15 row_mask:0xf bank_mask:0xf
	s_movk_i32 s14, 0xc00
	s_and_b64 vcc, exec, s[8:9]
	v_mov_b32_e32 v161, 0
	v_mov_b32_e32 v162, 0
	v_mov_b32_e32 v163, 0
	s_cbranch_vccnz .LBB0_1824
	ds_read_b128 v[160:163], v231 offset:512
	s_movk_i32 s14, 0x1400
.LBB0_1824:
	s_waitcnt lgkmcnt(0)
	v_cndmask_b32_e64 v165, v236, v165, s[10:11]
	v_cndmask_b32_e64 v164, v234, v164, s[10:11]
	v_cndmask_b32_e64 v167, v237, v167, s[10:11]
	v_cndmask_b32_e64 v166, v235, v166, s[10:11]
	s_waitcnt vmcnt(0)
	v_pk_fma_f32 v[164:165], v[152:153], v[164:165], v[156:157]
	v_pk_fma_f32 v[166:167], v[154:155], v[166:167], v[158:159]
	v_pk_fma_f32 v[164:165], v[124:125], v[148:149], v[164:165]
	v_pk_fma_f32 v[166:167], v[126:127], v[150:151], v[166:167]
	v_pk_fma_f32 v[164:165], v[140:141], v[186:187], v[164:165]
	v_pk_fma_f32 v[192:193], v[142:143], v[192:193], v[166:167]
	v_mul_f32_e32 v167, 0xbfb8aa3b, v164
	v_exp_f32_e32 v167, v167
	v_mul_f32_e32 v186, 0xbfb8aa3b, v165
	v_cndmask_b32_e64 v161, v240, v161, s[10:11]
	v_cndmask_b32_e64 v160, v238, v160, s[10:11]
	v_exp_f32_e32 v186, v186
	v_pk_fma_f32 v[160:161], v[136:137], v[160:161], v[144:145]
	v_add_f32_e32 v167, 1.0, v167
	v_pk_fma_f32 v[160:161], v[116:117], v[132:133], v[160:161]
	v_cndmask_b32_e64 v163, v241, v163, s[10:11]
	v_pk_fma_f32 v[160:161], v[128:129], v[184:185], v[160:161]
	v_mul_f32_e32 v185, 0xbfb8aa3b, v192
	v_rcp_f32_e32 v184, v167
	v_add_f32_e32 v167, 1.0, v186
	v_exp_f32_e32 v186, v185
	v_mul_f32_e32 v185, 0xbfb8aa3b, v193
	v_exp_f32_e32 v187, v185
	v_rcp_f32_e32 v185, v167
	v_add_f32_e32 v167, 1.0, v186
	v_rcp_f32_e32 v186, v167
	v_add_f32_e32 v167, 1.0, v187
	v_rcp_f32_e32 v187, v167
	v_cndmask_b32_e64 v162, v239, v162, s[10:11]
	v_pk_fma_f32 v[162:163], v[138:139], v[162:163], v[146:147]
	v_pk_mul_f32 v[164:165], v[164:165], v[184:185]
	s_lshl_b32 s12, s12, 8
	v_pk_fma_f32 v[162:163], v[118:119], v[134:135], v[162:163]
	v_pk_mul_f32 v[160:161], v[164:165], v[160:161]
	s_add_i32 s12, s12, s58
	v_pk_fma_f32 v[162:163], v[130:131], v[194:195], v[162:163]
	v_cvt_pk_bf16_f32 v184, v160, v161
	v_pk_mul_f32 v[160:161], v[192:193], v[186:187]
	v_add_u32_e32 v166, s12, v233
	v_pk_mul_f32 v[160:161], v[160:161], v[162:163]
	v_mov_b64_e32 v[162:163], s[18:19]
	s_movk_i32 s35, 0x1600
	v_cvt_pk_bf16_f32 v185, v160, v161
	v_mad_i64_i32 v[160:161], s[12:13], v166, s35, v[162:163]
	v_cmp_eq_u32_e64 s[12:13], 15, v233
	v_lshlrev_b64 v[164:165], 1, v[178:179]
	v_lshl_add_u64 v[160:161], v[160:161], 0, v[164:165]
; #define PG8_LAS __attribute__((address_space(3)))
; __device__ __forceinline__ unsigned pk2(float lo, float hi) { f32x2_pk v = {lo, hi}; bf16x2_pk b = __builtin_convertvector(v, bf16x2_pk); return __builtin_bit_cast(unsigned, b); }
; __device__ __forceinline__ float sigmoidf_(float x) { return __builtin_amdgcn_rcpf(1.0f + __expf(-x)); }
;     __device__ __forceinline__ void operator()(const f32x4 (&acc)[2][2][4][2], const Unit& u, int wr, int wc, int fr_, int fq_) const {
;     ...
;                 for (int m = 0; m < 4; ++m) { f32x4 cv[2];
; #pragma unroll
;                     for (int bj = 0; bj < 2; ++bj) {
;                         const f32x4 cur = acc[ai][bj][m][n];
;                         const f32x4 su = (fr == 15 && m > 0) ? acc[ai][bj][m > 0 ? m - 1 : 0][n] : cur;
;                         const f32x4 sd = (fr == 0 && m < 3) ? acc[ai][bj][m < 3 ? m + 1 : 3][n] : cur;
;                         f32x4 up, dn;
; #pragma unroll
;                         for (int e = 0; e < 4; ++e) { up[e] = __shfl(su[e], srcu); dn[e] = __shfl(sd[e], srcd); }
;                         if (m == 0) { f32x4 pv = (f32x4){0.f, 0.f, 0.f, 0.f}; if (sp >= 0) pv = *(const PG8_LAS f32x4*)(xch + sp * 256 + 128 * bj + cl + 4 * n); if (fr == 0) up = pv; }
;                         if (m == 3) { f32x4 nv = (f32x4){0.f, 0.f, 0.f, 0.f}; if (sn >= 0) nv = *(const PG8_LAS f32x4*)(xch + sn * 256 + 128 * bj + cl + 4 * n); if (fr == 15) dn = nv; }
;                         cv[bj] = bv[bj] + w0[bj] * up + w1[bj] * cur + w2[bj] * dn; }
;                     u32x2 hw; hw.x = pk2(cv[0][0] * sigmoidf_(cv[0][0]) * cv[1][0], cv[0][1] * sigmoidf_(cv[0][1]) * cv[1][1]); hw.y = pk2(cv[0][2] * sigmoidf_(cv[0][2]) * cv[1][2], cv[0][3] * sigmoidf_(cv[0][3]) * cv[1][3]);
;                     *(u32x2*)(H + (size_t)(u.pm * BM + ai * HALF + wr * 64 + m * 16 + fr) * 2816 + chg + 4 * n) = hw;
	v_cndmask_b32_e64 v125, v121, v125, s[12:13]
	v_cndmask_b32_e64 v124, v120, v124, s[12:13]
	s_nop 1
	v_mov_b32_dpp v124, v124 row_ror:1 row_mask:0xf bank_mask:0xf
	v_mov_b32_dpp v125, v125 row_ror:1 row_mask:0xf bank_mask:0xf
	v_cndmask_b32_e64 v127, v123, v127, s[12:13]
	v_cndmask_b32_e64 v167, v122, v126, s[12:13]
	v_cndmask_b32_e64 v192, v121, v109, s[10:11]
	v_cndmask_b32_e64 v126, v120, v108, s[10:11]
	global_store_dwordx2 v[160:161], v[184:185], off
	s_nop 0
	v_mov_b32_dpp v126, v126 row_ror:15 row_mask:0xf bank_mask:0xf
	v_mov_b32_dpp v184, v167 row_ror:1 row_mask:0xf bank_mask:0xf
	v_mov_b32_dpp v185, v127 row_ror:1 row_mask:0xf bank_mask:0xf
	v_mov_b32_dpp v127, v192 row_ror:15 row_mask:0xf bank_mask:0xf
	v_cndmask_b32_e64 v187, v123, v111, s[10:11]
	v_cndmask_b32_e64 v186, v122, v110, s[10:11]
	s_nop 1
	v_mov_b32_dpp v186, v186 row_ror:15 row_mask:0xf bank_mask:0xf
	v_mov_b32_dpp v187, v187 row_ror:15 row_mask:0xf bank_mask:0xf
	v_pk_fma_f32 v[124:125], v[152:153], v[124:125], v[156:157]
	v_pk_fma_f32 v[184:185], v[154:155], v[184:185], v[158:159]
	v_pk_fma_f32 v[124:125], v[120:121], v[148:149], v[124:125]
	v_cndmask_b32_e64 v119, v115, v119, s[12:13]
	v_pk_fma_f32 v[124:125], v[140:141], v[126:127], v[124:125]
	v_cndmask_b32_e64 v126, v114, v118, s[12:13]
	v_pk_fma_f32 v[184:185], v[122:123], v[150:151], v[184:185]
	s_nop 0
	v_mov_b32_dpp v126, v126 row_ror:1 row_mask:0xf bank_mask:0xf
	v_mov_b32_dpp v127, v119 row_ror:1 row_mask:0xf bank_mask:0xf
	v_pk_fma_f32 v[184:185], v[142:143], v[186:187], v[184:185]
	v_cndmask_b32_e64 v167, v115, v107, s[10:11]
	v_cndmask_b32_e64 v186, v114, v106, s[10:11]
	v_cndmask_b32_e64 v187, v113, v105, s[10:11]
	s_nop 1
	v_mov_b32_dpp v119, v187 row_ror:15 row_mask:0xf bank_mask:0xf
	v_mov_b32_dpp v186, v186 row_ror:15 row_mask:0xf bank_mask:0xf
	v_mov_b32_dpp v187, v167 row_ror:15 row_mask:0xf bank_mask:0xf
	v_cndmask_b32_e64 v117, v113, v117, s[12:13]
	v_cndmask_b32_e64 v116, v112, v116, s[12:13]
	s_nop 1
	v_mov_b32_dpp v116, v116 row_ror:1 row_mask:0xf bank_mask:0xf
	v_mov_b32_dpp v117, v117 row_ror:1 row_mask:0xf bank_mask:0xf
	v_cndmask_b32_e64 v118, v112, v104, s[10:11]
	v_pk_fma_f32 v[126:127], v[138:139], v[126:127], v[146:147]
	s_nop 0
	v_mov_b32_dpp v118, v118 row_ror:15 row_mask:0xf bank_mask:0xf
	v_pk_fma_f32 v[126:127], v[114:115], v[134:135], v[126:127]
	v_mul_f32_e32 v167, 0xbfb8aa3b, v124
	v_pk_fma_f32 v[126:127], v[130:131], v[186:187], v[126:127]
	v_exp_f32_e32 v167, v167
	v_mul_f32_e32 v186, 0xbfb8aa3b, v125
	v_exp_f32_e32 v186, v186
	v_pk_fma_f32 v[116:117], v[136:137], v[116:117], v[144:145]
	v_cndmask_b32_e64 v121, v109, v121, s[12:13]
	v_pk_fma_f32 v[116:117], v[112:113], v[132:133], v[116:117]
	v_cndmask_b32_e64 v122, v110, v122, s[12:13]
	v_pk_fma_f32 v[116:117], v[128:129], v[118:119], v[116:117]
	v_add_f32_e32 v118, 1.0, v167
	v_mul_f32_e32 v167, 0xbfb8aa3b, v184
	v_add_f32_e32 v119, 1.0, v186
	v_exp_f32_e32 v167, v167
	v_mul_f32_e32 v186, 0xbfb8aa3b, v185
	v_exp_f32_e32 v187, v186
	v_rcp_f32_e32 v118, v118
	v_rcp_f32_e32 v119, v119
	v_add_f32_e32 v167, 1.0, v167
	v_rcp_f32_e32 v186, v167
	v_add_f32_e32 v167, 1.0, v187
	v_rcp_f32_e32 v187, v167
	v_pk_mul_f32 v[118:119], v[124:125], v[118:119]
	v_mov_b32_dpp v122, v122 row_ror:1 row_mask:0xf bank_mask:0xf
	v_pk_mul_f32 v[116:117], v[118:119], v[116:117]
	v_cndmask_b32_e64 v125, v111, v103, s[10:11]
	v_cvt_pk_bf16_f32 v118, v116, v117
	v_pk_mul_f32 v[116:117], v[184:185], v[186:187]
	v_cndmask_b32_e64 v124, v110, v102, s[10:11]
	v_pk_mul_f32 v[116:117], v[116:117], v[126:127]
	v_cndmask_b32_e64 v126, v109, v101, s[10:11]
	v_cvt_pk_bf16_f32 v119, v116, v117
	v_add_u32_e32 v116, 16, v166
	v_mad_i64_i32 v[116:117], s[44:45], v116, s35, v[162:163]
	v_lshl_add_u64 v[116:117], v[116:117], 0, v[164:165]
	global_store_dwordx2 v[116:117], v[118:119], off
	v_cndmask_b32_e64 v119, v111, v123, s[12:13]
	v_cndmask_b32_e64 v118, v108, v120, s[12:13]
	s_nop 1
	v_mov_b32_dpp v118, v118 row_ror:1 row_mask:0xf bank_mask:0xf
	v_mov_b32_dpp v123, v119 row_ror:1 row_mask:0xf bank_mask:0xf
	v_mov_b32_dpp v119, v121 row_ror:1 row_mask:0xf bank_mask:0xf
	v_cndmask_b32_e64 v120, v108, v100, s[10:11]
	s_nop 1
	v_mov_b32_dpp v120, v120 row_ror:15 row_mask:0xf bank_mask:0xf
	v_mov_b32_dpp v121, v126 row_ror:15 row_mask:0xf bank_mask:0xf
	v_mov_b32_dpp v124, v124 row_ror:15 row_mask:0xf bank_mask:0xf
	v_mov_b32_dpp v125, v125 row_ror:15 row_mask:0xf bank_mask:0xf
	v_pk_fma_f32 v[118:119], v[152:153], v[118:119], v[156:157]
	v_pk_fma_f32 v[122:123], v[154:155], v[122:123], v[158:159]
	v_pk_fma_f32 v[118:119], v[108:109], v[148:149], v[118:119]
	v_cndmask_b32_e64 v115, v107, v115, s[12:13]
	v_pk_fma_f32 v[118:119], v[140:141], v[120:121], v[118:119]
	v_cndmask_b32_e64 v120, v106, v114, s[12:13]
	v_pk_fma_f32 v[122:123], v[110:111], v[150:151], v[122:123]
	s_nop 0
	v_mov_b32_dpp v120, v120 row_ror:1 row_mask:0xf bank_mask:0xf
	v_mov_b32_dpp v121, v115 row_ror:1 row_mask:0xf bank_mask:0xf
	v_pk_fma_f32 v[122:123], v[142:143], v[124:125], v[122:123]
	v_cndmask_b32_e64 v125, v107, v99, s[10:11]
	v_cndmask_b32_e64 v124, v106, v98, s[10:11]
	s_nop 1
	v_mov_b32_dpp v124, v124 row_ror:15 row_mask:0xf bank_mask:0xf
	v_mov_b32_dpp v125, v125 row_ror:15 row_mask:0xf bank_mask:0xf
	v_cndmask_b32_e64 v113, v105, v113, s[12:13]
	v_cndmask_b32_e64 v112, v104, v112, s[12:13]
	s_nop 1
	v_mov_b32_dpp v112, v112 row_ror:1 row_mask:0xf bank_mask:0xf
	v_mov_b32_dpp v113, v113 row_ror:1 row_mask:0xf bank_mask:0xf
	v_pk_fma_f32 v[120:121], v[138:139], v[120:121], v[146:147]
	v_cndmask_b32_e64 v126, v105, v97, s[10:11]
	v_cndmask_b32_e64 v114, v104, v96, s[10:11]
; #define PG8_LAS __attribute__((address_space(3)))
; __device__ __forceinline__ unsigned pk2(float lo, float hi) { f32x2_pk v = {lo, hi}; bf16x2_pk b = __builtin_convertvector(v, bf16x2_pk); return __builtin_bit_cast(unsigned, b); }
; __device__ __forceinline__ float sigmoidf_(float x) { return __builtin_amdgcn_rcpf(1.0f + __expf(-x)); }
;     __device__ __forceinline__ void operator()(const f32x4 (&acc)[2][2][4][2], const Unit& u, int wr, int wc, int fr_, int fq_) const {
;     ...
;                 for (int m = 0; m < 4; ++m) { f32x4 cv[2];
; #pragma unroll
;                     for (int bj = 0; bj < 2; ++bj) {
;                         const f32x4 cur = acc[ai][bj][m][n];
;                         const f32x4 su = (fr == 15 && m > 0) ? acc[ai][bj][m > 0 ? m - 1 : 0][n] : cur;
;                         const f32x4 sd = (fr == 0 && m < 3) ? acc[ai][bj][m < 3 ? m + 1 : 3][n] : cur;
;                         f32x4 up, dn;
; #pragma unroll
;                         for (int e = 0; e < 4; ++e) { up[e] = __shfl(su[e], srcu); dn[e] = __shfl(sd[e], srcd); }
;                         if (m == 0) { f32x4 pv = (f32x4){0.f, 0.f, 0.f, 0.f}; if (sp >= 0) pv = *(const PG8_LAS f32x4*)(xch + sp * 256 + 128 * bj + cl + 4 * n); if (fr == 0) up = pv; }
;                         if (m == 3) { f32x4 nv = (f32x4){0.f, 0.f, 0.f, 0.f}; if (sn >= 0) nv = *(const PG8_LAS f32x4*)(xch + sn * 256 + 128 * bj + cl + 4 * n); if (fr == 15) dn = nv; }
;                         cv[bj] = bv[bj] + w0[bj] * up + w1[bj] * cur + w2[bj] * dn; }
;                     u32x2 hw; hw.x = pk2(cv[0][0] * sigmoidf_(cv[0][0]) * cv[1][0], cv[0][1] * sigmoidf_(cv[0][1]) * cv[1][1]); hw.y = pk2(cv[0][2] * sigmoidf_(cv[0][2]) * cv[1][2], cv[0][3] * sigmoidf_(cv[0][3]) * cv[1][3]);
;                     *(u32x2*)(H + (size_t)(u.pm * BM + ai * HALF + wr * 64 + m * 16 + fr) * 2816 + chg + 4 * n) = hw;
	v_pk_fma_f32 v[120:121], v[106:107], v[134:135], v[120:121]
	s_nop 0
	v_mov_b32_dpp v114, v114 row_ror:15 row_mask:0xf bank_mask:0xf
	v_mov_b32_dpp v115, v126 row_ror:15 row_mask:0xf bank_mask:0xf
	v_pk_fma_f32 v[120:121], v[130:131], v[124:125], v[120:121]
	v_mul_f32_e32 v124, 0xbfb8aa3b, v118
	v_mul_f32_e32 v125, 0xbfb8aa3b, v119
	v_exp_f32_e32 v124, v124
	v_exp_f32_e32 v125, v125
	v_pk_fma_f32 v[112:113], v[136:137], v[112:113], v[144:145]
	v_cndmask_b32_e64 v109, v101, v109, s[12:13]
	v_pk_fma_f32 v[112:113], v[104:105], v[132:133], v[112:113]
	v_cndmask_b32_e64 v108, v100, v108, s[12:13]
	v_pk_fma_f32 v[112:113], v[128:129], v[114:115], v[112:113]
	v_add_f32_e32 v114, 1.0, v124
	v_add_f32_e32 v115, 1.0, v125
	v_mul_f32_e32 v124, 0xbfb8aa3b, v122
	v_mul_f32_e32 v125, 0xbfb8aa3b, v123
	v_exp_f32_e32 v124, v124
	v_exp_f32_e32 v125, v125
	v_rcp_f32_e32 v114, v114
	v_rcp_f32_e32 v115, v115
	v_add_f32_e32 v124, 1.0, v124
	v_add_f32_e32 v125, 1.0, v125
	v_rcp_f32_e32 v124, v124
	v_rcp_f32_e32 v125, v125
	v_pk_mul_f32 v[114:115], v[118:119], v[114:115]
	v_add_u32_e32 v126, s67, v232
	v_pk_mul_f32 v[112:113], v[114:115], v[112:113]
	v_cndmask_b32_e64 v118, v103, v111, s[12:13]
	v_cvt_pk_bf16_f32 v114, v112, v113
	v_pk_mul_f32 v[112:113], v[122:123], v[124:125]
	v_cndmask_b32_e64 v110, v102, v110, s[12:13]
	v_pk_mul_f32 v[112:113], v[112:113], v[120:121]
	v_mov_b32_dpp v124, v100 row_ror:15 row_mask:0xf bank_mask:0xf
	v_cvt_pk_bf16_f32 v115, v112, v113
	v_add_u32_e32 v112, 32, v166
	v_mad_i64_i32 v[112:113], s[44:45], v112, s35, v[162:163]
	v_lshl_add_u64 v[112:113], v[112:113], 0, v[164:165]
	global_store_dwordx2 v[112:113], v[114:115], off
	v_mov_b32_dpp v114, v108 row_ror:1 row_mask:0xf bank_mask:0xf
	v_mov_b32_dpp v115, v109 row_ror:1 row_mask:0xf bank_mask:0xf
	v_mov_b32_dpp v125, v101 row_ror:15 row_mask:0xf bank_mask:0xf
	v_mov_b32_dpp v122, v110 row_ror:1 row_mask:0xf bank_mask:0xf
	ds_read_b128 v[108:111], v126
	v_mov_b32_dpp v123, v118 row_ror:1 row_mask:0xf bank_mask:0xf
	v_cndmask_b32_e64 v105, v97, v105, s[12:13]
	v_cndmask_b32_e64 v104, v96, v104, s[12:13]
	v_mov_b32_dpp v127, v102 row_ror:15 row_mask:0xf bank_mask:0xf
	v_mov_b32_dpp v167, v103 row_ror:15 row_mask:0xf bank_mask:0xf
	v_cndmask_b32_e64 v107, v99, v107, s[12:13]
	v_cndmask_b32_e64 v106, v98, v106, s[12:13]
	v_mov_b32_dpp v104, v104 row_ror:1 row_mask:0xf bank_mask:0xf
	v_mov_b32_dpp v105, v105 row_ror:1 row_mask:0xf bank_mask:0xf
	v_mov_b32_dpp v106, v106 row_ror:1 row_mask:0xf bank_mask:0xf
	v_mov_b32_dpp v107, v107 row_ror:1 row_mask:0xf bank_mask:0xf
	s_waitcnt lgkmcnt(0)
	v_pk_fma_f32 v[114:115], v[152:153], v[114:115], v[156:157]
	ds_read_b128 v[118:121], v126 offset:512
	s_waitcnt lgkmcnt(0)
	v_cndmask_b32_e64 v109, v125, v109, s[12:13]
	v_cndmask_b32_e64 v108, v124, v108, s[12:13]
	v_pk_fma_f32 v[122:123], v[154:155], v[122:123], v[158:159]
	v_pk_fma_f32 v[100:101], v[100:101], v[148:149], v[114:115]
	v_cndmask_b32_e64 v111, v167, v111, s[12:13]
	v_cndmask_b32_e64 v110, v127, v110, s[12:13]
	v_pk_fma_f32 v[102:103], v[102:103], v[150:151], v[122:123]
	v_pk_fma_f32 v[100:101], v[140:141], v[108:109], v[100:101]
	v_pk_fma_f32 v[104:105], v[136:137], v[104:105], v[144:145]
	v_pk_fma_f32 v[102:103], v[142:143], v[110:111], v[102:103]
	v_mov_b32_dpp v108, v96 row_ror:15 row_mask:0xf bank_mask:0xf
	v_mov_b32_dpp v109, v97 row_ror:15 row_mask:0xf bank_mask:0xf
	v_pk_fma_f32 v[106:107], v[138:139], v[106:107], v[146:147]
	v_pk_fma_f32 v[96:97], v[96:97], v[132:133], v[104:105]
	v_mul_f32_e32 v104, 0xbfb8aa3b, v100
	v_mul_f32_e32 v105, 0xbfb8aa3b, v101
	v_mov_b32_dpp v110, v99 row_ror:15 row_mask:0xf bank_mask:0xf
	v_mov_b32_dpp v114, v98 row_ror:15 row_mask:0xf bank_mask:0xf
	v_pk_fma_f32 v[98:99], v[98:99], v[134:135], v[106:107]
	v_exp_f32_e32 v104, v104
	v_exp_f32_e32 v105, v105
	v_mul_f32_e32 v106, 0xbfb8aa3b, v102
	v_mul_f32_e32 v107, 0xbfb8aa3b, v103
	v_exp_f32_e32 v106, v106
	v_exp_f32_e32 v107, v107
	v_add_f32_e32 v104, 1.0, v104
	v_add_f32_e32 v105, 1.0, v105
	v_rcp_f32_e32 v104, v104
	v_rcp_f32_e32 v105, v105
	v_add_f32_e32 v106, 1.0, v106
	v_add_f32_e32 v107, 1.0, v107
	v_rcp_f32_e32 v106, v106
	v_rcp_f32_e32 v107, v107
	v_cndmask_b32_e64 v109, v109, v119, s[12:13]
	v_cndmask_b32_e64 v108, v108, v118, s[12:13]
	v_cndmask_b32_e64 v111, v110, v121, s[12:13]
	v_cndmask_b32_e64 v110, v114, v120, s[12:13]
	v_pk_fma_f32 v[96:97], v[128:129], v[108:109], v[96:97]
	v_pk_mul_f32 v[100:101], v[100:101], v[104:105]
	v_pk_fma_f32 v[98:99], v[130:131], v[110:111], v[98:99]
	v_pk_mul_f32 v[96:97], v[100:101], v[96:97]
	v_pk_mul_f32 v[100:101], v[102:103], v[106:107]
	v_cvt_pk_bf16_f32 v96, v96, v97
	v_pk_mul_f32 v[98:99], v[100:101], v[98:99]
	s_add_i32 s14, s14, 0
	v_cvt_pk_bf16_f32 v97, v98, v99
	v_add_u32_e32 v98, 48, v166
	v_mad_i64_i32 v[98:99], s[44:45], v98, s35, v[162:163]
	v_lshl_add_u64 v[104:105], v[98:99], 0, v[164:165]
	global_store_dwordx2 v[104:105], v[96:97], off
	v_add_u32_e32 v96, s14, v232
	v_add_u32_e32 v127, 0x20000, v96
	v_cndmask_b32_e64 v96, v93, v89, s[10:11]
	v_cndmask_b32_e64 v97, v92, v88, s[10:11]
	s_nop 1
	v_mov_b32_dpp v106, v97 row_ror:15 row_mask:0xf bank_mask:0xf
	v_mov_b32_dpp v107, v96 row_ror:15 row_mask:0xf bank_mask:0xf
	v_mov_b32_dpp v115, v94 row_ror:1 row_mask:0xf bank_mask:0xf
	ds_read_b128 v[96:99], v127
	v_mov_b32_dpp v118, v95 row_ror:1 row_mask:0xf bank_mask:0xf
	v_cndmask_b32_e64 v100, v95, v91, s[10:11]
	v_cndmask_b32_e64 v101, v94, v90, s[10:11]
	s_nop 1
	v_mov_b32_dpp v108, v101 row_ror:15 row_mask:0xf bank_mask:0xf
	v_mov_b32_dpp v109, v100 row_ror:15 row_mask:0xf bank_mask:0xf
	v_mov_b32_dpp v111, v92 row_ror:1 row_mask:0xf bank_mask:0xf
	v_mov_b32_dpp v114, v93 row_ror:1 row_mask:0xf bank_mask:0xf
	ds_read_b128 v[100:103], v127 offset:512
	s_waitcnt lgkmcnt(0)
; #define PG8_LAS __attribute__((address_space(3)))
; __device__ __forceinline__ unsigned pk2(float lo, float hi) { f32x2_pk v = {lo, hi}; bf16x2_pk b = __builtin_convertvector(v, bf16x2_pk); return __builtin_bit_cast(unsigned, b); }
; __device__ __forceinline__ float sigmoidf_(float x) { return __builtin_amdgcn_rcpf(1.0f + __expf(-x)); }
;     __device__ __forceinline__ void operator()(const f32x4 (&acc)[2][2][4][2], const Unit& u, int wr, int wc, int fr_, int fq_) const {
;     ...
;                 for (int m = 0; m < 4; ++m) { f32x4 cv[2];
; #pragma unroll
;                     for (int bj = 0; bj < 2; ++bj) {
;                         const f32x4 cur = acc[ai][bj][m][n];
;                         const f32x4 su = (fr == 15 && m > 0) ? acc[ai][bj][m > 0 ? m - 1 : 0][n] : cur;
;                         const f32x4 sd = (fr == 0 && m < 3) ? acc[ai][bj][m < 3 ? m + 1 : 3][n] : cur;
;                         f32x4 up, dn;
; #pragma unroll
;                         for (int e = 0; e < 4; ++e) { up[e] = __shfl(su[e], srcu); dn[e] = __shfl(sd[e], srcd); }
;                         if (m == 0) { f32x4 pv = (f32x4){0.f, 0.f, 0.f, 0.f}; if (sp >= 0) pv = *(const PG8_LAS f32x4*)(xch + sp * 256 + 128 * bj + cl + 4 * n); if (fr == 0) up = pv; }
;                         if (m == 3) { f32x4 nv = (f32x4){0.f, 0.f, 0.f, 0.f}; if (sn >= 0) nv = *(const PG8_LAS f32x4*)(xch + sn * 256 + 128 * bj + cl + 4 * n); if (fr == 15) dn = nv; }
;                         cv[bj] = bv[bj] + w0[bj] * up + w1[bj] * cur + w2[bj] * dn; }
;                     u32x2 hw; hw.x = pk2(cv[0][0] * sigmoidf_(cv[0][0]) * cv[1][0], cv[0][1] * sigmoidf_(cv[0][1]) * cv[1][1]); hw.y = pk2(cv[0][2] * sigmoidf_(cv[0][2]) * cv[1][2], cv[0][3] * sigmoidf_(cv[0][3]) * cv[1][3]);
;                     *(u32x2*)(H + (size_t)(u.pm * BM + ai * HALF + wr * 64 + m * 16 + fr) * 2816 + chg + 4 * n) = hw;
	v_cndmask_b32_e64 v99, v118, v99, s[10:11]
	v_cndmask_b32_e64 v98, v115, v98, s[10:11]
	v_pk_fma_f32 v[98:99], v[154:155], v[98:99], v[158:159]
	v_mov_b32_dpp v115, v86 row_ror:1 row_mask:0xf bank_mask:0xf
	v_mov_b32_dpp v118, v87 row_ror:1 row_mask:0xf bank_mask:0xf
	v_pk_fma_f32 v[98:99], v[94:95], v[150:151], v[98:99]
	v_cndmask_b32_e64 v97, v114, v97, s[10:11]
	v_pk_fma_f32 v[98:99], v[142:143], v[108:109], v[98:99]
	v_cndmask_b32_e64 v109, v87, v83, s[10:11]
	v_cndmask_b32_e64 v108, v86, v82, s[10:11]
	s_nop 1
	v_mov_b32_dpp v108, v108 row_ror:15 row_mask:0xf bank_mask:0xf
	v_mov_b32_dpp v109, v109 row_ror:15 row_mask:0xf bank_mask:0xf
	v_cndmask_b32_e64 v96, v111, v96, s[10:11]
	v_pk_fma_f32 v[96:97], v[152:153], v[96:97], v[156:157]
	v_mov_b32_dpp v111, v84 row_ror:1 row_mask:0xf bank_mask:0xf
	v_mov_b32_dpp v114, v85 row_ror:1 row_mask:0xf bank_mask:0xf
	v_cndmask_b32_e64 v103, v118, v103, s[10:11]
	v_cndmask_b32_e64 v102, v115, v102, s[10:11]
	v_pk_fma_f32 v[96:97], v[92:93], v[148:149], v[96:97]
	v_pk_fma_f32 v[102:103], v[138:139], v[102:103], v[146:147]
	v_pk_fma_f32 v[96:97], v[140:141], v[106:107], v[96:97]
	v_cndmask_b32_e64 v107, v85, v81, s[10:11]
	v_cndmask_b32_e64 v106, v84, v80, s[10:11]
	v_pk_fma_f32 v[102:103], v[86:87], v[134:135], v[102:103]
	s_nop 0
	v_mov_b32_dpp v106, v106 row_ror:15 row_mask:0xf bank_mask:0xf
	v_mov_b32_dpp v107, v107 row_ror:15 row_mask:0xf bank_mask:0xf
	v_pk_fma_f32 v[102:103], v[130:131], v[108:109], v[102:103]
	v_mul_f32_e32 v108, 0xbfb8aa3b, v96
	v_mul_f32_e32 v109, 0xbfb8aa3b, v97
	v_exp_f32_e32 v108, v108
	v_exp_f32_e32 v109, v109
	v_cndmask_b32_e64 v101, v114, v101, s[10:11]
	v_cndmask_b32_e64 v100, v111, v100, s[10:11]
	v_pk_fma_f32 v[100:101], v[136:137], v[100:101], v[144:145]
	v_add_u32_e32 v110, 0x80, v166
	v_pk_fma_f32 v[100:101], v[84:85], v[132:133], v[100:101]
	v_cndmask_b32_e64 v93, v89, v93, s[12:13]
	v_pk_fma_f32 v[100:101], v[128:129], v[106:107], v[100:101]
	v_add_f32_e32 v106, 1.0, v108
	v_add_f32_e32 v107, 1.0, v109
	v_mul_f32_e32 v108, 0xbfb8aa3b, v98
	v_mul_f32_e32 v109, 0xbfb8aa3b, v99
	v_exp_f32_e32 v108, v108
	v_exp_f32_e32 v109, v109
	v_rcp_f32_e32 v106, v106
	v_rcp_f32_e32 v107, v107
	v_add_f32_e32 v108, 1.0, v108
	v_add_f32_e32 v109, 1.0, v109
	v_rcp_f32_e32 v108, v108
	v_rcp_f32_e32 v109, v109
	v_pk_mul_f32 v[96:97], v[96:97], v[106:107]
	v_cndmask_b32_e64 v92, v88, v92, s[12:13]
	v_pk_mul_f32 v[96:97], v[96:97], v[100:101]
	v_pk_mul_f32 v[98:99], v[98:99], v[108:109]
	v_cvt_pk_bf16_f32 v96, v96, v97
	v_pk_mul_f32 v[98:99], v[98:99], v[102:103]
	v_mov_b32_dpp v92, v92 row_ror:1 row_mask:0xf bank_mask:0xf
	v_cvt_pk_bf16_f32 v97, v98, v99
	v_mad_i64_i32 v[98:99], s[14:15], v110, s35, v[162:163]
	v_lshl_add_u64 v[106:107], v[98:99], 0, v[164:165]
	v_mov_b32_dpp v93, v93 row_ror:1 row_mask:0xf bank_mask:0xf
	global_store_dwordx2 v[106:107], v[96:97], off
	v_cndmask_b32_e64 v95, v91, v95, s[12:13]
	v_cndmask_b32_e64 v96, v90, v94, s[12:13]
	v_cndmask_b32_e64 v100, v89, v77, s[10:11]
	v_cndmask_b32_e64 v94, v88, v76, s[10:11]
	s_nop 1
	v_mov_b32_dpp v94, v94 row_ror:15 row_mask:0xf bank_mask:0xf
	v_mov_b32_dpp v96, v96 row_ror:1 row_mask:0xf bank_mask:0xf
	v_mov_b32_dpp v97, v95 row_ror:1 row_mask:0xf bank_mask:0xf
	v_mov_b32_dpp v95, v100 row_ror:15 row_mask:0xf bank_mask:0xf
	v_cndmask_b32_e64 v99, v91, v79, s[10:11]
	v_cndmask_b32_e64 v98, v90, v78, s[10:11]
	s_nop 1
	v_mov_b32_dpp v98, v98 row_ror:15 row_mask:0xf bank_mask:0xf
	v_mov_b32_dpp v99, v99 row_ror:15 row_mask:0xf bank_mask:0xf
	v_pk_fma_f32 v[92:93], v[152:153], v[92:93], v[156:157]
	v_pk_fma_f32 v[96:97], v[154:155], v[96:97], v[158:159]
	v_pk_fma_f32 v[92:93], v[88:89], v[148:149], v[92:93]
	v_cndmask_b32_e64 v87, v83, v87, s[12:13]
	v_pk_fma_f32 v[92:93], v[140:141], v[94:95], v[92:93]
	v_cndmask_b32_e64 v94, v82, v86, s[12:13]
	v_pk_fma_f32 v[96:97], v[90:91], v[150:151], v[96:97]
	s_nop 0
	v_mov_b32_dpp v94, v94 row_ror:1 row_mask:0xf bank_mask:0xf
	v_mov_b32_dpp v95, v87 row_ror:1 row_mask:0xf bank_mask:0xf
	v_pk_fma_f32 v[96:97], v[142:143], v[98:99], v[96:97]
	v_cndmask_b32_e64 v99, v83, v75, s[10:11]
	v_cndmask_b32_e64 v98, v82, v74, s[10:11]
	s_nop 1
	v_mov_b32_dpp v98, v98 row_ror:15 row_mask:0xf bank_mask:0xf
	v_mov_b32_dpp v99, v99 row_ror:15 row_mask:0xf bank_mask:0xf
	v_cndmask_b32_e64 v85, v81, v85, s[12:13]
	v_cndmask_b32_e64 v84, v80, v84, s[12:13]
	s_nop 1
	v_mov_b32_dpp v84, v84 row_ror:1 row_mask:0xf bank_mask:0xf
	v_mov_b32_dpp v85, v85 row_ror:1 row_mask:0xf bank_mask:0xf
	v_pk_fma_f32 v[94:95], v[138:139], v[94:95], v[146:147]
	v_cndmask_b32_e64 v100, v81, v73, s[10:11]
	v_cndmask_b32_e64 v86, v80, v72, s[10:11]
	v_pk_fma_f32 v[94:95], v[82:83], v[134:135], v[94:95]
	s_nop 0
	v_mov_b32_dpp v86, v86 row_ror:15 row_mask:0xf bank_mask:0xf
	v_mov_b32_dpp v87, v100 row_ror:15 row_mask:0xf bank_mask:0xf
	v_pk_fma_f32 v[94:95], v[130:131], v[98:99], v[94:95]
	v_mul_f32_e32 v98, 0xbfb8aa3b, v92
	v_mul_f32_e32 v99, 0xbfb8aa3b, v93
	v_exp_f32_e32 v98, v98
	v_exp_f32_e32 v99, v99
	v_pk_fma_f32 v[84:85], v[136:137], v[84:85], v[144:145]
	v_cndmask_b32_e64 v83, v75, v83, s[12:13]
	v_pk_fma_f32 v[84:85], v[80:81], v[132:133], v[84:85]
	v_cndmask_b32_e64 v81, v73, v81, s[12:13]
	v_pk_fma_f32 v[84:85], v[128:129], v[86:87], v[84:85]
	v_add_f32_e32 v86, 1.0, v98
	v_add_f32_e32 v87, 1.0, v99
	v_mul_f32_e32 v98, 0xbfb8aa3b, v96
	v_mul_f32_e32 v99, 0xbfb8aa3b, v97
	v_exp_f32_e32 v98, v98
	v_exp_f32_e32 v99, v99
	v_rcp_f32_e32 v86, v86
	v_rcp_f32_e32 v87, v87
	v_add_f32_e32 v98, 1.0, v98
	v_add_f32_e32 v99, 1.0, v99
	v_rcp_f32_e32 v98, v98
	v_rcp_f32_e32 v99, v99
	v_pk_mul_f32 v[86:87], v[92:93], v[86:87]
; #define PG8_LAS __attribute__((address_space(3)))
; __device__ __forceinline__ unsigned pk2(float lo, float hi) { f32x2_pk v = {lo, hi}; bf16x2_pk b = __builtin_convertvector(v, bf16x2_pk); return __builtin_bit_cast(unsigned, b); }
; __device__ __forceinline__ float sigmoidf_(float x) { return __builtin_amdgcn_rcpf(1.0f + __expf(-x)); }
;     __device__ __forceinline__ void operator()(const f32x4 (&acc)[2][2][4][2], const Unit& u, int wr, int wc, int fr_, int fq_) const {
;     ...
;                 for (int m = 0; m < 4; ++m) { f32x4 cv[2];
; #pragma unroll
;                     for (int bj = 0; bj < 2; ++bj) {
;                         const f32x4 cur = acc[ai][bj][m][n];
;                         const f32x4 su = (fr == 15 && m > 0) ? acc[ai][bj][m > 0 ? m - 1 : 0][n] : cur;
;                         const f32x4 sd = (fr == 0 && m < 3) ? acc[ai][bj][m < 3 ? m + 1 : 3][n] : cur;
;                         f32x4 up, dn;
; #pragma unroll
;                         for (int e = 0; e < 4; ++e) { up[e] = __shfl(su[e], srcu); dn[e] = __shfl(sd[e], srcd); }
;                         if (m == 0) { f32x4 pv = (f32x4){0.f, 0.f, 0.f, 0.f}; if (sp >= 0) pv = *(const PG8_LAS f32x4*)(xch + sp * 256 + 128 * bj + cl + 4 * n); if (fr == 0) up = pv; }
;                         if (m == 3) { f32x4 nv = (f32x4){0.f, 0.f, 0.f, 0.f}; if (sn >= 0) nv = *(const PG8_LAS f32x4*)(xch + sn * 256 + 128 * bj + cl + 4 * n); if (fr == 15) dn = nv; }
;                         cv[bj] = bv[bj] + w0[bj] * up + w1[bj] * cur + w2[bj] * dn; }
;                     u32x2 hw; hw.x = pk2(cv[0][0] * sigmoidf_(cv[0][0]) * cv[1][0], cv[0][1] * sigmoidf_(cv[0][1]) * cv[1][1]); hw.y = pk2(cv[0][2] * sigmoidf_(cv[0][2]) * cv[1][2], cv[0][3] * sigmoidf_(cv[0][3]) * cv[1][3]);
;                     *(u32x2*)(H + (size_t)(u.pm * BM + ai * HALF + wr * 64 + m * 16 + fr) * 2816 + chg + 4 * n) = hw;
	v_cndmask_b32_e64 v93, v77, v69, s[10:11]
	v_pk_mul_f32 v[84:85], v[86:87], v[84:85]
	v_pk_mul_f32 v[86:87], v[96:97], v[98:99]
	v_cvt_pk_bf16_f32 v84, v84, v85
	v_pk_mul_f32 v[86:87], v[86:87], v[94:95]
	v_cndmask_b32_e64 v92, v78, v70, s[10:11]
	v_cvt_pk_bf16_f32 v85, v86, v87
	v_add_u32_e32 v86, 0x90, v166
	v_mad_i64_i32 v[86:87], s[14:15], v86, s35, v[162:163]
	v_lshl_add_u64 v[108:109], v[86:87], 0, v[164:165]
	global_store_dwordx2 v[108:109], v[84:85], off
	v_cndmask_b32_e64 v85, v79, v91, s[12:13]
	v_cndmask_b32_e64 v87, v78, v90, s[12:13]
	v_cndmask_b32_e64 v90, v77, v89, s[12:13]
	v_cndmask_b32_e64 v84, v76, v88, s[12:13]
	s_nop 1
	v_mov_b32_dpp v84, v84 row_ror:1 row_mask:0xf bank_mask:0xf
	v_mov_b32_dpp v89, v85 row_ror:1 row_mask:0xf bank_mask:0xf
	v_mov_b32_dpp v85, v90 row_ror:1 row_mask:0xf bank_mask:0xf
	v_cndmask_b32_e64 v86, v76, v68, s[10:11]
	s_nop 1
	v_mov_b32_dpp v86, v86 row_ror:15 row_mask:0xf bank_mask:0xf
	v_mov_b32_dpp v88, v87 row_ror:1 row_mask:0xf bank_mask:0xf
	v_mov_b32_dpp v87, v93 row_ror:15 row_mask:0xf bank_mask:0xf
	v_cndmask_b32_e64 v91, v79, v71, s[10:11]
	v_mov_b32_dpp v90, v92 row_ror:15 row_mask:0xf bank_mask:0xf
	s_nop 0
	v_mov_b32_dpp v91, v91 row_ror:15 row_mask:0xf bank_mask:0xf
	v_pk_fma_f32 v[84:85], v[152:153], v[84:85], v[156:157]
	v_pk_fma_f32 v[88:89], v[154:155], v[88:89], v[158:159]
	v_pk_fma_f32 v[84:85], v[76:77], v[148:149], v[84:85]
	v_pk_fma_f32 v[88:89], v[78:79], v[150:151], v[88:89]
	v_pk_fma_f32 v[84:85], v[140:141], v[86:87], v[84:85]
	v_cndmask_b32_e64 v86, v74, v82, s[12:13]
	s_nop 1
	v_mov_b32_dpp v86, v86 row_ror:1 row_mask:0xf bank_mask:0xf
	v_mov_b32_dpp v87, v83 row_ror:1 row_mask:0xf bank_mask:0xf
	v_pk_fma_f32 v[88:89], v[142:143], v[90:91], v[88:89]
	v_cndmask_b32_e64 v91, v75, v67, s[10:11]
	v_cndmask_b32_e64 v90, v74, v66, s[10:11]
	s_nop 1
	v_mov_b32_dpp v90, v90 row_ror:15 row_mask:0xf bank_mask:0xf
	v_mov_b32_dpp v91, v91 row_ror:15 row_mask:0xf bank_mask:0xf
	v_cndmask_b32_e64 v80, v72, v80, s[12:13]
	s_nop 1
	v_mov_b32_dpp v80, v80 row_ror:1 row_mask:0xf bank_mask:0xf
	v_mov_b32_dpp v81, v81 row_ror:1 row_mask:0xf bank_mask:0xf
	v_pk_fma_f32 v[86:87], v[138:139], v[86:87], v[146:147]
	v_cndmask_b32_e64 v92, v73, v65, s[10:11]
	v_cndmask_b32_e64 v82, v72, v64, s[10:11]
	v_pk_fma_f32 v[86:87], v[74:75], v[134:135], v[86:87]
	s_nop 0
	v_mov_b32_dpp v82, v82 row_ror:15 row_mask:0xf bank_mask:0xf
	v_mov_b32_dpp v83, v92 row_ror:15 row_mask:0xf bank_mask:0xf
	v_pk_fma_f32 v[86:87], v[130:131], v[90:91], v[86:87]
	v_mul_f32_e32 v90, 0xbfb8aa3b, v84
	v_mul_f32_e32 v91, 0xbfb8aa3b, v85
	v_exp_f32_e32 v90, v90
	v_exp_f32_e32 v91, v91
	v_pk_fma_f32 v[80:81], v[136:137], v[80:81], v[144:145]
	v_cndmask_b32_e64 v79, v71, v79, s[12:13]
	v_pk_fma_f32 v[80:81], v[72:73], v[132:133], v[80:81]
	v_cndmask_b32_e64 v78, v70, v78, s[12:13]
	v_pk_fma_f32 v[80:81], v[128:129], v[82:83], v[80:81]
	v_add_f32_e32 v82, 1.0, v90
	v_add_f32_e32 v83, 1.0, v91
	v_mul_f32_e32 v90, 0xbfb8aa3b, v88
	v_mul_f32_e32 v91, 0xbfb8aa3b, v89
	v_exp_f32_e32 v90, v90
	v_exp_f32_e32 v91, v91
	v_rcp_f32_e32 v82, v82
	v_rcp_f32_e32 v83, v83
	v_add_f32_e32 v90, 1.0, v90
	v_add_f32_e32 v91, 1.0, v91
	v_rcp_f32_e32 v90, v90
	v_rcp_f32_e32 v91, v91
	v_pk_mul_f32 v[82:83], v[84:85], v[82:83]
	v_cndmask_b32_e64 v77, v69, v77, s[12:13]
	v_pk_mul_f32 v[80:81], v[82:83], v[80:81]
	v_pk_mul_f32 v[82:83], v[88:89], v[90:91]
	v_cvt_pk_bf16_f32 v80, v80, v81
	v_pk_mul_f32 v[82:83], v[82:83], v[86:87]
	v_cndmask_b32_e64 v76, v68, v76, s[12:13]
	v_cvt_pk_bf16_f32 v81, v82, v83
	v_add_u32_e32 v82, 0xa0, v166
	v_mad_i64_i32 v[82:83], s[14:15], v82, s35, v[162:163]
	v_lshl_add_u64 v[110:111], v[82:83], 0, v[164:165]
	v_mov_b32_dpp v84, v76 row_ror:1 row_mask:0xf bank_mask:0xf
	v_mov_b32_dpp v88, v68 row_ror:15 row_mask:0xf bank_mask:0xf
	v_mov_b32_dpp v85, v77 row_ror:1 row_mask:0xf bank_mask:0xf
	v_mov_b32_dpp v90, v69 row_ror:15 row_mask:0xf bank_mask:0xf
	v_mov_b32_dpp v86, v78 row_ror:1 row_mask:0xf bank_mask:0xf
	v_mov_b32_dpp v89, v70 row_ror:15 row_mask:0xf bank_mask:0xf
	v_mov_b32_dpp v87, v79 row_ror:1 row_mask:0xf bank_mask:0xf
	v_mov_b32_dpp v91, v71 row_ror:15 row_mask:0xf bank_mask:0xf
	global_store_dwordx2 v[110:111], v[80:81], off
	v_cndmask_b32_e64 v77, 0, 1, s[26:27]
	s_movk_i32 s37, 0x1600
	v_add_u32_e32 v162, s68, v232
	v_mov_b32_e32 v76, 0
	v_cmp_ne_u32_e64 s[14:15], 1, v77
	s_andn2_b64 vcc, exec, s[26:27]
	v_mov_b32_e32 v80, 0
	v_mov_b32_e32 v81, 0
	v_mov_b32_e32 v82, 0
	v_mov_b32_e32 v83, 0
	s_cbranch_vccnz .LBB0_1826
	ds_read_b128 v[80:83], v162
.LBB0_1826:
	v_cndmask_b32_e64 v75, v67, v75, s[12:13]
	v_cndmask_b32_e64 v74, v66, v74, s[12:13]
	v_cndmask_b32_e64 v73, v65, v73, s[12:13]
	v_cndmask_b32_e64 v72, v64, v72, s[12:13]
	s_nop 1
	v_mov_b32_dpp v72, v72 row_ror:1 row_mask:0xf bank_mask:0xf
	v_mov_b32_dpp v92, v64 row_ror:15 row_mask:0xf bank_mask:0xf
	v_mov_b32_dpp v73, v73 row_ror:1 row_mask:0xf bank_mask:0xf
	v_mov_b32_dpp v94, v65 row_ror:15 row_mask:0xf bank_mask:0xf
	v_mov_b32_dpp v74, v74 row_ror:1 row_mask:0xf bank_mask:0xf
	v_mov_b32_dpp v93, v66 row_ror:15 row_mask:0xf bank_mask:0xf
	v_mov_b32_dpp v75, v75 row_ror:1 row_mask:0xf bank_mask:0xf
	v_mov_b32_dpp v95, v67 row_ror:15 row_mask:0xf bank_mask:0xf
	s_and_b64 vcc, exec, s[14:15]
	v_mov_b32_e32 v77, 0
	v_mov_b32_e32 v78, 0
	v_mov_b32_e32 v79, 0
	s_cbranch_vccnz .LBB0_1828
	ds_read_b128 v[76:79], v162 offset:512
; #define PG8_LAS __attribute__((address_space(3)))
; __device__ __forceinline__ float sigmoidf_(float x) { return __builtin_amdgcn_rcpf(1.0f + __expf(-x)); }
;     __device__ __forceinline__ void operator()(const f32x4 (&acc)[2][2][4][2], const Unit& u, int wr, int wc, int fr_, int fq_) const {
;     ...
;         for (int n = 0; n < 2; ++n) {
;             f32x4 w0[2], w1[2], w2[2], bv[2];
; #pragma unroll
;             for (int bj = 0; bj < 2; ++bj) { const int wcol = bj * 2816 + chg + 4 * n; w0[bj] = *(const f32x4*)(cw + wcol); w1[bj] = *(const f32x4*)(cw + 5632 + wcol); w2[bj] = *(const f32x4*)(cw + 2 * 5632 + wcol); bv[bj] = *(const f32x4*)(cb + wcol); }
; #pragma unroll
;             for (int ai = 0; ai < 2; ++ai) {
;                 const int sp = (wr == 1) ? ((ai * 2 + 0) * 2 + 1) : (ai == 1 ? ((0 * 2 + 1) * 2 + 1) : -1);
;                 const int sn = (wr == 0) ? ((ai * 2 + 1) * 2 + 0) : (ai == 0 ? ((1 * 2 + 0) * 2 + 0) : -1);
; #pragma unroll
;                 for (int m = 0; m < 4; ++m) { f32x4 cv[2];
; #pragma unroll
;                     for (int bj = 0; bj < 2; ++bj) {
;                         const f32x4 cur = acc[ai][bj][m][n];
;                         const f32x4 su = (fr == 15 && m > 0) ? acc[ai][bj][m > 0 ? m - 1 : 0][n] : cur;
;                         const f32x4 sd = (fr == 0 && m < 3) ? acc[ai][bj][m < 3 ? m + 1 : 3][n] : cur;
;                         f32x4 up, dn;
; #pragma unroll
;                         for (int e = 0; e < 4; ++e) { up[e] = __shfl(su[e], srcu); dn[e] = __shfl(sd[e], srcd); }
;                         if (m == 0) { f32x4 pv = (f32x4){0.f, 0.f, 0.f, 0.f}; if (sp >= 0) pv = *(const PG8_LAS f32x4*)(xch + sp * 256 + 128 * bj + cl + 4 * n); if (fr == 0) up = pv; }
;                         if (m == 3) { f32x4 nv = (f32x4){0.f, 0.f, 0.f, 0.f}; if (sn >= 0) nv = *(const PG8_LAS f32x4*)(xch + sn * 256 + 128 * bj + cl + 4 * n); if (fr == 15) dn = nv; }
;                         cv[bj] = bv[bj] + w0[bj] * up + w1[bj] * cur + w2[bj] * dn; }
;                     u32x2 hw; hw.x = pk2(cv[0][0] * sigmoidf_(cv[0][0]) * cv[1][0], cv[0][1] * sigmoidf_(cv[0][1]) * cv[1][1]); hw.y = pk2(cv[0][2] * sigmoidf_(cv[0][2]) * cv[1][2], cv[0][3] * sigmoidf_(cv[0][3]) * cv[1][3]);
;                     *(u32x2*)(H + (size_t)(u.pm * BM + ai * HALF + wr * 64 + m * 16 + fr) * 2816 + chg + 4 * n) = hw;
.LBB0_1828:
	s_waitcnt lgkmcnt(0)
	v_pk_fma_f32 v[84:85], v[152:153], v[84:85], v[156:157]
	v_cndmask_b32_e64 v81, v90, v81, s[12:13]
	v_cndmask_b32_e64 v80, v88, v80, s[12:13]
	v_pk_fma_f32 v[86:87], v[154:155], v[86:87], v[158:159]
	v_pk_fma_f32 v[68:69], v[68:69], v[148:149], v[84:85]
	v_cndmask_b32_e64 v83, v91, v83, s[12:13]
	v_cndmask_b32_e64 v82, v89, v82, s[12:13]
	v_pk_fma_f32 v[70:71], v[70:71], v[150:151], v[86:87]
	v_pk_fma_f32 v[68:69], v[140:141], v[80:81], v[68:69]
	v_pk_fma_f32 v[72:73], v[136:137], v[72:73], v[144:145]
	v_pk_fma_f32 v[70:71], v[142:143], v[82:83], v[70:71]
	v_pk_fma_f32 v[74:75], v[138:139], v[74:75], v[146:147]
	v_pk_fma_f32 v[64:65], v[64:65], v[132:133], v[72:73]
	v_mul_f32_e32 v72, 0xbfb8aa3b, v68
	v_mul_f32_e32 v73, 0xbfb8aa3b, v69
	v_pk_fma_f32 v[66:67], v[66:67], v[134:135], v[74:75]
	v_exp_f32_e32 v72, v72
	v_exp_f32_e32 v73, v73
	v_mul_f32_e32 v74, 0xbfb8aa3b, v70
	v_mul_f32_e32 v75, 0xbfb8aa3b, v71
	v_exp_f32_e32 v74, v74
	v_exp_f32_e32 v75, v75
	v_add_f32_e32 v72, 1.0, v72
	v_add_f32_e32 v73, 1.0, v73
	v_rcp_f32_e32 v72, v72
	v_rcp_f32_e32 v73, v73
	v_add_f32_e32 v74, 1.0, v74
	v_add_f32_e32 v75, 1.0, v75
	v_rcp_f32_e32 v74, v74
	v_rcp_f32_e32 v75, v75
	v_cndmask_b32_e64 v77, v94, v77, s[12:13]
	v_cndmask_b32_e64 v76, v92, v76, s[12:13]
	v_cndmask_b32_e64 v79, v95, v79, s[12:13]
	v_cndmask_b32_e64 v78, v93, v78, s[12:13]
	v_pk_fma_f32 v[64:65], v[128:129], v[76:77], v[64:65]
	v_pk_mul_f32 v[68:69], v[68:69], v[72:73]
	v_pk_fma_f32 v[66:67], v[130:131], v[78:79], v[66:67]
	v_pk_mul_f32 v[64:65], v[68:69], v[64:65]
	v_pk_mul_f32 v[68:69], v[70:71], v[74:75]
	v_cvt_pk_bf16_f32 v64, v64, v65
	v_pk_mul_f32 v[66:67], v[68:69], v[66:67]
	v_add_u32_e32 v68, 0xb0, v166
	v_cvt_pk_bf16_f32 v65, v66, v67
	v_mov_b64_e32 v[66:67], s[18:19]
	v_mad_i64_i32 v[66:67], s[44:45], v68, s37, v[66:67]
	v_lshl_add_u64 v[114:115], v[178:179], 1, v[66:67]
	global_store_dwordx2 v[114:115], v[64:65], off
	v_or_b32_e32 v64, 4, v178
	v_ashrrev_i32_e32 v65, 31, v64
	v_lshlrev_b64 v[64:65], 2, v[64:65]
	v_lshl_add_u64 v[66:67], s[28:29], 0, v[64:65]
	v_lshl_add_u64 v[64:65], s[30:31], 0, v[64:65]
	global_load_dwordx4 v[88:91], v[180:181], off offset:16
	global_load_dwordx4 v[84:87], v[66:67], off
	global_load_dwordx4 v[72:75], v[64:65], off
	global_load_dwordx4 v[92:95], v[182:183], off offset:16
	v_add_u32_e32 v64, 0xb04, v178
	v_ashrrev_i32_e32 v65, 31, v64
	v_lshlrev_b64 v[80:81], 2, v[64:65]
	v_lshl_add_u64 v[64:65], s[22:23], 0, v[80:81]
	v_lshl_add_u64 v[66:67], s[28:29], 0, v[80:81]
	global_load_dwordx4 v[76:79], v[64:65], off
	global_load_dwordx4 v[68:71], v[66:67], off
	v_lshl_add_u64 v[64:65], s[30:31], 0, v[80:81]
	v_lshl_add_u64 v[80:81], s[24:25], 0, v[80:81]
	global_load_dwordx4 v[64:67], v[64:65], off
	v_cndmask_b32_e64 v96, v63, v59, s[10:11]
	global_load_dwordx4 v[80:83], v[80:81], off
	v_cndmask_b32_e64 v97, v62, v58, s[10:11]
	v_cndmask_b32_e64 v98, v61, v57, s[10:11]
	v_cndmask_b32_e64 v99, v60, v56, s[10:11]
	v_mov_b32_dpp v128, v60 row_ror:1 row_mask:0xf bank_mask:0xf
	s_nop 0
	v_mov_b32_dpp v120, v99 row_ror:15 row_mask:0xf bank_mask:0xf
	v_mov_b32_dpp v130, v61 row_ror:1 row_mask:0xf bank_mask:0xf
	v_mov_b32_dpp v121, v98 row_ror:15 row_mask:0xf bank_mask:0xf
	v_mov_b32_dpp v129, v62 row_ror:1 row_mask:0xf bank_mask:0xf
	v_mov_b32_dpp v122, v97 row_ror:15 row_mask:0xf bank_mask:0xf
	v_mov_b32_dpp v131, v63 row_ror:1 row_mask:0xf bank_mask:0xf
	v_mov_b32_dpp v123, v96 row_ror:15 row_mask:0xf bank_mask:0xf
	v_mov_b32_e32 v96, 0
	s_and_b64 vcc, exec, s[8:9]
	v_mov_b32_e32 v100, 0
	v_mov_b32_e32 v101, 0
	v_mov_b32_e32 v102, 0
	v_mov_b32_e32 v103, 0
	s_cbranch_vccnz .LBB0_1830
	ds_read_b128 v[100:103], v231 offset:16
.LBB0_1830:
	v_cndmask_b32_e64 v97, v55, v51, s[10:11]
	v_cndmask_b32_e64 v98, v54, v50, s[10:11]
	v_cndmask_b32_e64 v99, v53, v49, s[10:11]
	v_cndmask_b32_e64 v118, v52, v48, s[10:11]
	v_mov_b32_dpp v132, v52 row_ror:1 row_mask:0xf bank_mask:0xf
	s_nop 0
	v_mov_b32_dpp v118, v118 row_ror:15 row_mask:0xf bank_mask:0xf
	v_mov_b32_dpp v134, v53 row_ror:1 row_mask:0xf bank_mask:0xf
	v_mov_b32_dpp v119, v99 row_ror:15 row_mask:0xf bank_mask:0xf
	v_mov_b32_dpp v133, v54 row_ror:1 row_mask:0xf bank_mask:0xf
	v_mov_b32_dpp v124, v98 row_ror:15 row_mask:0xf bank_mask:0xf
	v_mov_b32_dpp v135, v55 row_ror:1 row_mask:0xf bank_mask:0xf
	v_mov_b32_dpp v125, v97 row_ror:15 row_mask:0xf bank_mask:0xf
	s_and_b64 vcc, exec, s[8:9]
	v_mov_b32_e32 v97, 0
	v_mov_b32_e32 v98, 0
	v_mov_b32_e32 v99, 0
	s_cbranch_vccnz .LBB0_1832
	ds_read_b128 v[96:99], v231 offset:528
; #define PG8_LAS __attribute__((address_space(3)))
; __device__ __forceinline__ unsigned pk2(float lo, float hi) { f32x2_pk v = {lo, hi}; bf16x2_pk b = __builtin_convertvector(v, bf16x2_pk); return __builtin_bit_cast(unsigned, b); }
; __device__ __forceinline__ float sigmoidf_(float x) { return __builtin_amdgcn_rcpf(1.0f + __expf(-x)); }
;     __device__ __forceinline__ void operator()(const f32x4 (&acc)[2][2][4][2], const Unit& u, int wr, int wc, int fr_, int fq_) const {
;     ...
;                 for (int m = 0; m < 4; ++m) { f32x4 cv[2];
; #pragma unroll
;                     for (int bj = 0; bj < 2; ++bj) {
;                         const f32x4 cur = acc[ai][bj][m][n];
;                         const f32x4 su = (fr == 15 && m > 0) ? acc[ai][bj][m > 0 ? m - 1 : 0][n] : cur;
;                         const f32x4 sd = (fr == 0 && m < 3) ? acc[ai][bj][m < 3 ? m + 1 : 3][n] : cur;
;                         f32x4 up, dn;
; #pragma unroll
;                         for (int e = 0; e < 4; ++e) { up[e] = __shfl(su[e], srcu); dn[e] = __shfl(sd[e], srcd); }
;                         if (m == 0) { f32x4 pv = (f32x4){0.f, 0.f, 0.f, 0.f}; if (sp >= 0) pv = *(const PG8_LAS f32x4*)(xch + sp * 256 + 128 * bj + cl + 4 * n); if (fr == 0) up = pv; }
;                         if (m == 3) { f32x4 nv = (f32x4){0.f, 0.f, 0.f, 0.f}; if (sn >= 0) nv = *(const PG8_LAS f32x4*)(xch + sn * 256 + 128 * bj + cl + 4 * n); if (fr == 15) dn = nv; }
;                         cv[bj] = bv[bj] + w0[bj] * up + w1[bj] * cur + w2[bj] * dn; }
;                     u32x2 hw; hw.x = pk2(cv[0][0] * sigmoidf_(cv[0][0]) * cv[1][0], cv[0][1] * sigmoidf_(cv[0][1]) * cv[1][1]); hw.y = pk2(cv[0][2] * sigmoidf_(cv[0][2]) * cv[1][2], cv[0][3] * sigmoidf_(cv[0][3]) * cv[1][3]);
;                     *(u32x2*)(H + (size_t)(u.pm * BM + ai * HALF + wr * 64 + m * 16 + fr) * 2816 + chg + 4 * n) = hw;
.LBB0_1832:
	s_waitcnt lgkmcnt(0)
	v_cndmask_b32_e64 v101, v130, v101, s[10:11]
	v_cndmask_b32_e64 v100, v128, v100, s[10:11]
	s_waitcnt vmcnt(4)
	v_pk_fma_f32 v[100:101], v[88:89], v[100:101], v[92:93]
	v_cndmask_b32_e64 v103, v131, v103, s[10:11]
	v_pk_fma_f32 v[100:101], v[60:61], v[84:85], v[100:101]
	v_cndmask_b32_e64 v102, v129, v102, s[10:11]
	v_pk_fma_f32 v[100:101], v[72:73], v[120:121], v[100:101]
	v_pk_fma_f32 v[102:103], v[90:91], v[102:103], v[94:95]
	v_mul_f32_e32 v120, 0xbfb8aa3b, v100
	v_mul_f32_e32 v121, 0xbfb8aa3b, v101
	v_exp_f32_e32 v120, v120
	v_exp_f32_e32 v121, v121
	v_cndmask_b32_e64 v97, v134, v97, s[10:11]
	v_cndmask_b32_e64 v96, v132, v96, s[10:11]
	v_pk_fma_f32 v[102:103], v[62:63], v[86:87], v[102:103]
	s_waitcnt vmcnt(0)
	v_pk_fma_f32 v[96:97], v[76:77], v[96:97], v[80:81]
	v_pk_fma_f32 v[102:103], v[74:75], v[122:123], v[102:103]
	v_pk_fma_f32 v[96:97], v[52:53], v[68:69], v[96:97]
	v_cndmask_b32_e64 v99, v135, v99, s[10:11]
	v_pk_fma_f32 v[96:97], v[64:65], v[118:119], v[96:97]
	v_add_f32_e32 v118, 1.0, v120
	v_add_f32_e32 v119, 1.0, v121
	v_mul_f32_e32 v120, 0xbfb8aa3b, v102
	v_mul_f32_e32 v121, 0xbfb8aa3b, v103
	v_exp_f32_e32 v120, v120
	v_exp_f32_e32 v121, v121
	v_rcp_f32_e32 v118, v118
	v_rcp_f32_e32 v119, v119
	v_add_f32_e32 v120, 1.0, v120
	v_add_f32_e32 v121, 1.0, v121
	v_rcp_f32_e32 v120, v120
	v_rcp_f32_e32 v121, v121
	v_cndmask_b32_e64 v98, v133, v98, s[10:11]
	v_pk_fma_f32 v[98:99], v[78:79], v[98:99], v[82:83]
	v_pk_mul_f32 v[100:101], v[100:101], v[118:119]
	v_pk_fma_f32 v[98:99], v[54:55], v[70:71], v[98:99]
	v_pk_mul_f32 v[96:97], v[100:101], v[96:97]
	v_pk_fma_f32 v[98:99], v[66:67], v[124:125], v[98:99]
	v_pk_mul_f32 v[100:101], v[102:103], v[120:121]
	v_cndmask_b32_e64 v61, v57, v61, s[12:13]
	v_pk_mul_f32 v[98:99], v[100:101], v[98:99]
	v_cndmask_b32_e64 v60, v56, v60, s[12:13]
	v_cvt_pk_bf16_f32 v96, v96, v97
	v_cvt_pk_bf16_f32 v97, v98, v99
	v_mov_b32_dpp v60, v60 row_ror:1 row_mask:0xf bank_mask:0xf
	v_mov_b32_dpp v61, v61 row_ror:1 row_mask:0xf bank_mask:0xf
	global_store_dwordx2 v[160:161], v[96:97], off offset:8
	v_cndmask_b32_e64 v63, v59, v63, s[12:13]
	v_cndmask_b32_e64 v96, v58, v62, s[12:13]
	v_cndmask_b32_e64 v100, v57, v45, s[10:11]
	v_cndmask_b32_e64 v62, v56, v44, s[10:11]
	s_nop 1
	v_mov_b32_dpp v62, v62 row_ror:15 row_mask:0xf bank_mask:0xf
	v_mov_b32_dpp v96, v96 row_ror:1 row_mask:0xf bank_mask:0xf
	v_mov_b32_dpp v97, v63 row_ror:1 row_mask:0xf bank_mask:0xf
	v_mov_b32_dpp v63, v100 row_ror:15 row_mask:0xf bank_mask:0xf
	v_cndmask_b32_e64 v99, v59, v47, s[10:11]
	v_cndmask_b32_e64 v98, v58, v46, s[10:11]
	s_nop 1
	v_mov_b32_dpp v98, v98 row_ror:15 row_mask:0xf bank_mask:0xf
	v_mov_b32_dpp v99, v99 row_ror:15 row_mask:0xf bank_mask:0xf
	v_pk_fma_f32 v[60:61], v[88:89], v[60:61], v[92:93]
	v_pk_fma_f32 v[96:97], v[90:91], v[96:97], v[94:95]
	v_pk_fma_f32 v[60:61], v[56:57], v[84:85], v[60:61]
	v_cndmask_b32_e64 v55, v51, v55, s[12:13]
	v_pk_fma_f32 v[60:61], v[72:73], v[62:63], v[60:61]
	v_cndmask_b32_e64 v62, v50, v54, s[12:13]
	v_pk_fma_f32 v[96:97], v[58:59], v[86:87], v[96:97]
	s_nop 0
	v_mov_b32_dpp v62, v62 row_ror:1 row_mask:0xf bank_mask:0xf
	v_mov_b32_dpp v63, v55 row_ror:1 row_mask:0xf bank_mask:0xf
	v_pk_fma_f32 v[96:97], v[74:75], v[98:99], v[96:97]
	v_cndmask_b32_e64 v99, v51, v43, s[10:11]
	v_cndmask_b32_e64 v98, v50, v42, s[10:11]
	s_nop 1
	v_mov_b32_dpp v98, v98 row_ror:15 row_mask:0xf bank_mask:0xf
	v_mov_b32_dpp v99, v99 row_ror:15 row_mask:0xf bank_mask:0xf
	v_cndmask_b32_e64 v53, v49, v53, s[12:13]
	v_cndmask_b32_e64 v52, v48, v52, s[12:13]
	s_nop 1
	v_mov_b32_dpp v52, v52 row_ror:1 row_mask:0xf bank_mask:0xf
	v_mov_b32_dpp v53, v53 row_ror:1 row_mask:0xf bank_mask:0xf
	v_pk_fma_f32 v[62:63], v[78:79], v[62:63], v[82:83]
	v_cndmask_b32_e64 v100, v49, v41, s[10:11]
	v_cndmask_b32_e64 v54, v48, v40, s[10:11]
	v_pk_fma_f32 v[62:63], v[50:51], v[70:71], v[62:63]
	s_nop 0
	v_mov_b32_dpp v54, v54 row_ror:15 row_mask:0xf bank_mask:0xf
	v_mov_b32_dpp v55, v100 row_ror:15 row_mask:0xf bank_mask:0xf
	v_pk_fma_f32 v[62:63], v[66:67], v[98:99], v[62:63]
	v_mul_f32_e32 v98, 0xbfb8aa3b, v60
	v_mul_f32_e32 v99, 0xbfb8aa3b, v61
	v_exp_f32_e32 v98, v98
	v_exp_f32_e32 v99, v99
	v_pk_fma_f32 v[52:53], v[76:77], v[52:53], v[80:81]
	v_cndmask_b32_e64 v51, v43, v51, s[12:13]
	v_pk_fma_f32 v[52:53], v[48:49], v[68:69], v[52:53]
	v_cndmask_b32_e64 v49, v41, v49, s[12:13]
	v_pk_fma_f32 v[52:53], v[64:65], v[54:55], v[52:53]
	v_add_f32_e32 v54, 1.0, v98
	v_add_f32_e32 v55, 1.0, v99
	v_mul_f32_e32 v98, 0xbfb8aa3b, v96
	v_mul_f32_e32 v99, 0xbfb8aa3b, v97
	v_exp_f32_e32 v98, v98
	v_exp_f32_e32 v99, v99
	v_rcp_f32_e32 v54, v54
	v_rcp_f32_e32 v55, v55
	v_add_f32_e32 v98, 1.0, v98
	v_add_f32_e32 v99, 1.0, v99
	v_rcp_f32_e32 v98, v98
	v_rcp_f32_e32 v99, v99
	v_pk_mul_f32 v[54:55], v[60:61], v[54:55]
	v_cndmask_b32_e64 v61, v45, v37, s[10:11]
	v_pk_mul_f32 v[52:53], v[54:55], v[52:53]
	v_pk_mul_f32 v[54:55], v[96:97], v[98:99]
	v_cvt_pk_bf16_f32 v52, v52, v53
	v_pk_mul_f32 v[54:55], v[54:55], v[62:63]
	v_cndmask_b32_e64 v60, v46, v38, s[10:11]
	v_cvt_pk_bf16_f32 v53, v54, v55
	global_store_dwordx2 v[116:117], v[52:53], off offset:8
	v_cndmask_b32_e64 v53, v47, v59, s[12:13]
	v_cndmask_b32_e64 v55, v46, v58, s[12:13]
	v_cndmask_b32_e64 v58, v45, v57, s[12:13]
	v_cndmask_b32_e64 v52, v44, v56, s[12:13]
	s_nop 1
	v_mov_b32_dpp v52, v52 row_ror:1 row_mask:0xf bank_mask:0xf
	v_mov_b32_dpp v57, v53 row_ror:1 row_mask:0xf bank_mask:0xf
	v_mov_b32_dpp v53, v58 row_ror:1 row_mask:0xf bank_mask:0xf
	v_cndmask_b32_e64 v54, v44, v36, s[10:11]
	s_nop 1
	v_mov_b32_dpp v54, v54 row_ror:15 row_mask:0xf bank_mask:0xf
; #define PG8_LAS __attribute__((address_space(3)))
; __device__ __forceinline__ unsigned pk2(float lo, float hi) { f32x2_pk v = {lo, hi}; bf16x2_pk b = __builtin_convertvector(v, bf16x2_pk); return __builtin_bit_cast(unsigned, b); }
; __device__ __forceinline__ float sigmoidf_(float x) { return __builtin_amdgcn_rcpf(1.0f + __expf(-x)); }
;     __device__ __forceinline__ void operator()(const f32x4 (&acc)[2][2][4][2], const Unit& u, int wr, int wc, int fr_, int fq_) const {
;     ...
;                 for (int m = 0; m < 4; ++m) { f32x4 cv[2];
; #pragma unroll
;                     for (int bj = 0; bj < 2; ++bj) {
;                         const f32x4 cur = acc[ai][bj][m][n];
;                         const f32x4 su = (fr == 15 && m > 0) ? acc[ai][bj][m > 0 ? m - 1 : 0][n] : cur;
;                         const f32x4 sd = (fr == 0 && m < 3) ? acc[ai][bj][m < 3 ? m + 1 : 3][n] : cur;
;                         f32x4 up, dn;
; #pragma unroll
;                         for (int e = 0; e < 4; ++e) { up[e] = __shfl(su[e], srcu); dn[e] = __shfl(sd[e], srcd); }
;                         if (m == 0) { f32x4 pv = (f32x4){0.f, 0.f, 0.f, 0.f}; if (sp >= 0) pv = *(const PG8_LAS f32x4*)(xch + sp * 256 + 128 * bj + cl + 4 * n); if (fr == 0) up = pv; }
;                         if (m == 3) { f32x4 nv = (f32x4){0.f, 0.f, 0.f, 0.f}; if (sn >= 0) nv = *(const PG8_LAS f32x4*)(xch + sn * 256 + 128 * bj + cl + 4 * n); if (fr == 15) dn = nv; }
;                         cv[bj] = bv[bj] + w0[bj] * up + w1[bj] * cur + w2[bj] * dn; }
;                     u32x2 hw; hw.x = pk2(cv[0][0] * sigmoidf_(cv[0][0]) * cv[1][0], cv[0][1] * sigmoidf_(cv[0][1]) * cv[1][1]); hw.y = pk2(cv[0][2] * sigmoidf_(cv[0][2]) * cv[1][2], cv[0][3] * sigmoidf_(cv[0][3]) * cv[1][3]);
;                     *(u32x2*)(H + (size_t)(u.pm * BM + ai * HALF + wr * 64 + m * 16 + fr) * 2816 + chg + 4 * n) = hw;
	v_mov_b32_dpp v56, v55 row_ror:1 row_mask:0xf bank_mask:0xf
	v_mov_b32_dpp v55, v61 row_ror:15 row_mask:0xf bank_mask:0xf
	v_cndmask_b32_e64 v59, v47, v39, s[10:11]
	v_mov_b32_dpp v58, v60 row_ror:15 row_mask:0xf bank_mask:0xf
	s_nop 0
	v_mov_b32_dpp v59, v59 row_ror:15 row_mask:0xf bank_mask:0xf
	v_pk_fma_f32 v[52:53], v[88:89], v[52:53], v[92:93]
	v_pk_fma_f32 v[56:57], v[90:91], v[56:57], v[94:95]
	v_pk_fma_f32 v[52:53], v[44:45], v[84:85], v[52:53]
	v_pk_fma_f32 v[56:57], v[46:47], v[86:87], v[56:57]
	v_pk_fma_f32 v[52:53], v[72:73], v[54:55], v[52:53]
	v_cndmask_b32_e64 v54, v42, v50, s[12:13]
	s_nop 1
	v_mov_b32_dpp v54, v54 row_ror:1 row_mask:0xf bank_mask:0xf
	v_mov_b32_dpp v55, v51 row_ror:1 row_mask:0xf bank_mask:0xf
	v_pk_fma_f32 v[56:57], v[74:75], v[58:59], v[56:57]
	v_cndmask_b32_e64 v59, v43, v35, s[10:11]
	v_cndmask_b32_e64 v58, v42, v34, s[10:11]
	s_nop 1
	v_mov_b32_dpp v58, v58 row_ror:15 row_mask:0xf bank_mask:0xf
	v_mov_b32_dpp v59, v59 row_ror:15 row_mask:0xf bank_mask:0xf
	v_cndmask_b32_e64 v48, v40, v48, s[12:13]
	s_nop 1
	v_mov_b32_dpp v48, v48 row_ror:1 row_mask:0xf bank_mask:0xf
	v_mov_b32_dpp v49, v49 row_ror:1 row_mask:0xf bank_mask:0xf
	v_pk_fma_f32 v[54:55], v[78:79], v[54:55], v[82:83]
	v_cndmask_b32_e64 v60, v41, v33, s[10:11]
	v_cndmask_b32_e64 v50, v40, v32, s[10:11]
	v_pk_fma_f32 v[54:55], v[42:43], v[70:71], v[54:55]
	s_nop 0
	v_mov_b32_dpp v50, v50 row_ror:15 row_mask:0xf bank_mask:0xf
	v_mov_b32_dpp v51, v60 row_ror:15 row_mask:0xf bank_mask:0xf
	v_pk_fma_f32 v[54:55], v[66:67], v[58:59], v[54:55]
	v_mul_f32_e32 v58, 0xbfb8aa3b, v52
	v_mul_f32_e32 v59, 0xbfb8aa3b, v53
	v_exp_f32_e32 v58, v58
	v_exp_f32_e32 v59, v59
	v_pk_fma_f32 v[48:49], v[76:77], v[48:49], v[80:81]
	v_cndmask_b32_e64 v45, v37, v45, s[12:13]
	v_pk_fma_f32 v[48:49], v[40:41], v[68:69], v[48:49]
	v_cndmask_b32_e64 v44, v36, v44, s[12:13]
	v_pk_fma_f32 v[48:49], v[64:65], v[50:51], v[48:49]
	v_add_f32_e32 v50, 1.0, v58
	v_add_f32_e32 v51, 1.0, v59
	v_mul_f32_e32 v58, 0xbfb8aa3b, v56
	v_mul_f32_e32 v59, 0xbfb8aa3b, v57
	v_exp_f32_e32 v58, v58
	v_exp_f32_e32 v59, v59
	v_rcp_f32_e32 v50, v50
	v_rcp_f32_e32 v51, v51
	v_add_f32_e32 v58, 1.0, v58
	v_add_f32_e32 v59, 1.0, v59
	v_rcp_f32_e32 v58, v58
	v_rcp_f32_e32 v59, v59
	v_pk_mul_f32 v[50:51], v[52:53], v[50:51]
	v_cndmask_b32_e64 v46, v38, v46, s[12:13]
	v_pk_mul_f32 v[48:49], v[50:51], v[48:49]
	v_pk_mul_f32 v[50:51], v[56:57], v[58:59]
	v_cvt_pk_bf16_f32 v48, v48, v49
	v_pk_mul_f32 v[50:51], v[50:51], v[54:55]
	v_mov_b32_dpp v52, v44 row_ror:1 row_mask:0xf bank_mask:0xf
	v_cvt_pk_bf16_f32 v49, v50, v51
	global_store_dwordx2 v[112:113], v[48:49], off offset:8
	v_cndmask_b32_e64 v48, v39, v47, s[12:13]
	v_mov_b32_dpp v53, v45 row_ror:1 row_mask:0xf bank_mask:0xf
	v_mov_b32_dpp v56, v36 row_ror:15 row_mask:0xf bank_mask:0xf
	v_mov_b32_dpp v57, v37 row_ror:15 row_mask:0xf bank_mask:0xf
	v_mov_b32_dpp v54, v46 row_ror:1 row_mask:0xf bank_mask:0xf
	ds_read_b128 v[44:47], v126 offset:16
	v_mov_b32_dpp v55, v48 row_ror:1 row_mask:0xf bank_mask:0xf
	v_cndmask_b32_e64 v41, v33, v41, s[12:13]
	v_cndmask_b32_e64 v40, v32, v40, s[12:13]
	v_mov_b32_dpp v58, v38 row_ror:15 row_mask:0xf bank_mask:0xf
	v_mov_b32_dpp v59, v39 row_ror:15 row_mask:0xf bank_mask:0xf
	v_cndmask_b32_e64 v43, v35, v43, s[12:13]
	v_cndmask_b32_e64 v42, v34, v42, s[12:13]
	v_mov_b32_dpp v40, v40 row_ror:1 row_mask:0xf bank_mask:0xf
	v_mov_b32_dpp v41, v41 row_ror:1 row_mask:0xf bank_mask:0xf
	v_mov_b32_dpp v42, v42 row_ror:1 row_mask:0xf bank_mask:0xf
	v_mov_b32_dpp v43, v43 row_ror:1 row_mask:0xf bank_mask:0xf
	s_waitcnt lgkmcnt(0)
	v_pk_fma_f32 v[52:53], v[88:89], v[52:53], v[92:93]
	ds_read_b128 v[48:51], v126 offset:528
	s_waitcnt lgkmcnt(0)
	v_cndmask_b32_e64 v45, v57, v45, s[12:13]
	v_cndmask_b32_e64 v44, v56, v44, s[12:13]
	v_pk_fma_f32 v[54:55], v[90:91], v[54:55], v[94:95]
	v_pk_fma_f32 v[36:37], v[36:37], v[84:85], v[52:53]
	v_cndmask_b32_e64 v47, v59, v47, s[12:13]
	v_cndmask_b32_e64 v46, v58, v46, s[12:13]
	v_pk_fma_f32 v[38:39], v[38:39], v[86:87], v[54:55]
	v_pk_fma_f32 v[36:37], v[72:73], v[44:45], v[36:37]
	v_pk_fma_f32 v[40:41], v[76:77], v[40:41], v[80:81]
	v_pk_fma_f32 v[38:39], v[74:75], v[46:47], v[38:39]
	v_mov_b32_dpp v44, v32 row_ror:15 row_mask:0xf bank_mask:0xf
	v_mov_b32_dpp v45, v33 row_ror:15 row_mask:0xf bank_mask:0xf
	v_pk_fma_f32 v[42:43], v[78:79], v[42:43], v[82:83]
	v_pk_fma_f32 v[32:33], v[32:33], v[68:69], v[40:41]
	v_mul_f32_e32 v40, 0xbfb8aa3b, v36
	v_mul_f32_e32 v41, 0xbfb8aa3b, v37
	v_mov_b32_dpp v46, v35 row_ror:15 row_mask:0xf bank_mask:0xf
	v_mov_b32_dpp v52, v34 row_ror:15 row_mask:0xf bank_mask:0xf
	v_pk_fma_f32 v[34:35], v[34:35], v[70:71], v[42:43]
	v_exp_f32_e32 v40, v40
	v_exp_f32_e32 v41, v41
	v_mul_f32_e32 v42, 0xbfb8aa3b, v38
	v_mul_f32_e32 v43, 0xbfb8aa3b, v39
	v_exp_f32_e32 v42, v42
	v_exp_f32_e32 v43, v43
	v_add_f32_e32 v40, 1.0, v40
	v_add_f32_e32 v41, 1.0, v41
	v_rcp_f32_e32 v40, v40
	v_rcp_f32_e32 v41, v41
	v_add_f32_e32 v42, 1.0, v42
	v_add_f32_e32 v43, 1.0, v43
	v_rcp_f32_e32 v42, v42
	v_rcp_f32_e32 v43, v43
	v_cndmask_b32_e64 v45, v45, v49, s[12:13]
	v_cndmask_b32_e64 v44, v44, v48, s[12:13]
	v_cndmask_b32_e64 v47, v46, v51, s[12:13]
	v_cndmask_b32_e64 v46, v52, v50, s[12:13]
	v_pk_fma_f32 v[32:33], v[64:65], v[44:45], v[32:33]
	v_pk_mul_f32 v[36:37], v[36:37], v[40:41]
	v_pk_fma_f32 v[34:35], v[66:67], v[46:47], v[34:35]
	v_pk_mul_f32 v[32:33], v[36:37], v[32:33]
	v_pk_mul_f32 v[36:37], v[38:39], v[42:43]
	v_cvt_pk_bf16_f32 v32, v32, v33
	v_pk_mul_f32 v[34:35], v[36:37], v[34:35]
	v_mov_b32_dpp v46, v30 row_ror:1 row_mask:0xf bank_mask:0xf
	v_cvt_pk_bf16_f32 v33, v34, v35
	global_store_dwordx2 v[104:105], v[32:33], off offset:8
	v_cndmask_b32_e64 v32, v29, v25, s[10:11]
	v_cndmask_b32_e64 v33, v28, v24, s[10:11]
	s_nop 1
	v_mov_b32_dpp v40, v33 row_ror:15 row_mask:0xf bank_mask:0xf
	v_mov_b32_dpp v41, v32 row_ror:15 row_mask:0xf bank_mask:0xf
	ds_read_b128 v[32:35], v127 offset:16
	v_mov_b32_dpp v47, v31 row_ror:1 row_mask:0xf bank_mask:0xf
	v_cndmask_b32_e64 v36, v31, v27, s[10:11]
	v_cndmask_b32_e64 v37, v30, v26, s[10:11]
	s_nop 1
	v_mov_b32_dpp v42, v37 row_ror:15 row_mask:0xf bank_mask:0xf
	v_mov_b32_dpp v43, v36 row_ror:15 row_mask:0xf bank_mask:0xf
	v_mov_b32_dpp v44, v28 row_ror:1 row_mask:0xf bank_mask:0xf
	v_mov_b32_dpp v45, v29 row_ror:1 row_mask:0xf bank_mask:0xf
	ds_read_b128 v[36:39], v127 offset:528
	s_waitcnt lgkmcnt(0)
; #define PG8_LAS __attribute__((address_space(3)))
; __device__ __forceinline__ unsigned pk2(float lo, float hi) { f32x2_pk v = {lo, hi}; bf16x2_pk b = __builtin_convertvector(v, bf16x2_pk); return __builtin_bit_cast(unsigned, b); }
; __device__ __forceinline__ float sigmoidf_(float x) { return __builtin_amdgcn_rcpf(1.0f + __expf(-x)); }
;     __device__ __forceinline__ void operator()(const f32x4 (&acc)[2][2][4][2], const Unit& u, int wr, int wc, int fr_, int fq_) const {
;     ...
;                 for (int m = 0; m < 4; ++m) { f32x4 cv[2];
; #pragma unroll
;                     for (int bj = 0; bj < 2; ++bj) {
;                         const f32x4 cur = acc[ai][bj][m][n];
;                         const f32x4 su = (fr == 15 && m > 0) ? acc[ai][bj][m > 0 ? m - 1 : 0][n] : cur;
;                         const f32x4 sd = (fr == 0 && m < 3) ? acc[ai][bj][m < 3 ? m + 1 : 3][n] : cur;
;                         f32x4 up, dn;
; #pragma unroll
;                         for (int e = 0; e < 4; ++e) { up[e] = __shfl(su[e], srcu); dn[e] = __shfl(sd[e], srcd); }
;                         if (m == 0) { f32x4 pv = (f32x4){0.f, 0.f, 0.f, 0.f}; if (sp >= 0) pv = *(const PG8_LAS f32x4*)(xch + sp * 256 + 128 * bj + cl + 4 * n); if (fr == 0) up = pv; }
;                         if (m == 3) { f32x4 nv = (f32x4){0.f, 0.f, 0.f, 0.f}; if (sn >= 0) nv = *(const PG8_LAS f32x4*)(xch + sn * 256 + 128 * bj + cl + 4 * n); if (fr == 15) dn = nv; }
;                         cv[bj] = bv[bj] + w0[bj] * up + w1[bj] * cur + w2[bj] * dn; }
;                     u32x2 hw; hw.x = pk2(cv[0][0] * sigmoidf_(cv[0][0]) * cv[1][0], cv[0][1] * sigmoidf_(cv[0][1]) * cv[1][1]); hw.y = pk2(cv[0][2] * sigmoidf_(cv[0][2]) * cv[1][2], cv[0][3] * sigmoidf_(cv[0][3]) * cv[1][3]);
;                     *(u32x2*)(H + (size_t)(u.pm * BM + ai * HALF + wr * 64 + m * 16 + fr) * 2816 + chg + 4 * n) = hw;
	v_cndmask_b32_e64 v35, v47, v35, s[10:11]
	v_cndmask_b32_e64 v34, v46, v34, s[10:11]
	v_pk_fma_f32 v[34:35], v[90:91], v[34:35], v[94:95]
	v_mov_b32_dpp v46, v22 row_ror:1 row_mask:0xf bank_mask:0xf
	v_mov_b32_dpp v47, v23 row_ror:1 row_mask:0xf bank_mask:0xf
	v_pk_fma_f32 v[34:35], v[30:31], v[86:87], v[34:35]
	v_cndmask_b32_e64 v33, v45, v33, s[10:11]
	v_pk_fma_f32 v[34:35], v[74:75], v[42:43], v[34:35]
	v_cndmask_b32_e64 v43, v23, v19, s[10:11]
	v_cndmask_b32_e64 v42, v22, v18, s[10:11]
	s_nop 1
	v_mov_b32_dpp v42, v42 row_ror:15 row_mask:0xf bank_mask:0xf
	v_mov_b32_dpp v43, v43 row_ror:15 row_mask:0xf bank_mask:0xf
	v_cndmask_b32_e64 v32, v44, v32, s[10:11]
	v_pk_fma_f32 v[32:33], v[88:89], v[32:33], v[92:93]
	v_mov_b32_dpp v44, v20 row_ror:1 row_mask:0xf bank_mask:0xf
	v_mov_b32_dpp v45, v21 row_ror:1 row_mask:0xf bank_mask:0xf
	v_cndmask_b32_e64 v39, v47, v39, s[10:11]
	v_cndmask_b32_e64 v38, v46, v38, s[10:11]
	v_pk_fma_f32 v[32:33], v[28:29], v[84:85], v[32:33]
	v_pk_fma_f32 v[38:39], v[78:79], v[38:39], v[82:83]
	v_pk_fma_f32 v[32:33], v[72:73], v[40:41], v[32:33]
	v_cndmask_b32_e64 v41, v21, v17, s[10:11]
	v_cndmask_b32_e64 v40, v20, v16, s[10:11]
	v_pk_fma_f32 v[38:39], v[22:23], v[70:71], v[38:39]
	s_nop 0
	v_mov_b32_dpp v40, v40 row_ror:15 row_mask:0xf bank_mask:0xf
	v_mov_b32_dpp v41, v41 row_ror:15 row_mask:0xf bank_mask:0xf
	v_pk_fma_f32 v[38:39], v[66:67], v[42:43], v[38:39]
	v_mul_f32_e32 v42, 0xbfb8aa3b, v32
	v_mul_f32_e32 v43, 0xbfb8aa3b, v33
	v_exp_f32_e32 v42, v42
	v_exp_f32_e32 v43, v43
	v_cndmask_b32_e64 v37, v45, v37, s[10:11]
	v_cndmask_b32_e64 v36, v44, v36, s[10:11]
	v_pk_fma_f32 v[36:37], v[76:77], v[36:37], v[80:81]
	v_cndmask_b32_e64 v29, v25, v29, s[12:13]
	v_pk_fma_f32 v[36:37], v[20:21], v[68:69], v[36:37]
	v_cndmask_b32_e64 v28, v24, v28, s[12:13]
	v_pk_fma_f32 v[36:37], v[64:65], v[40:41], v[36:37]
	v_add_f32_e32 v40, 1.0, v42
	v_add_f32_e32 v41, 1.0, v43
	v_mul_f32_e32 v42, 0xbfb8aa3b, v34
	v_mul_f32_e32 v43, 0xbfb8aa3b, v35
	v_exp_f32_e32 v42, v42
	v_exp_f32_e32 v43, v43
	v_rcp_f32_e32 v40, v40
	v_rcp_f32_e32 v41, v41
	v_add_f32_e32 v42, 1.0, v42
	v_add_f32_e32 v43, 1.0, v43
	v_rcp_f32_e32 v42, v42
	v_rcp_f32_e32 v43, v43
	v_pk_mul_f32 v[32:33], v[32:33], v[40:41]
	v_mov_b32_dpp v28, v28 row_ror:1 row_mask:0xf bank_mask:0xf
	v_pk_mul_f32 v[32:33], v[32:33], v[36:37]
	v_pk_mul_f32 v[34:35], v[34:35], v[42:43]
	v_cvt_pk_bf16_f32 v32, v32, v33
	v_pk_mul_f32 v[34:35], v[34:35], v[38:39]
	v_mov_b32_dpp v29, v29 row_ror:1 row_mask:0xf bank_mask:0xf
	v_cvt_pk_bf16_f32 v33, v34, v35
	global_store_dwordx2 v[106:107], v[32:33], off offset:8
	v_cndmask_b32_e64 v31, v27, v31, s[12:13]
	v_cndmask_b32_e64 v32, v26, v30, s[12:13]
	v_cndmask_b32_e64 v36, v25, v13, s[10:11]
	v_cndmask_b32_e64 v30, v24, v12, s[10:11]
	s_nop 1
	v_mov_b32_dpp v30, v30 row_ror:15 row_mask:0xf bank_mask:0xf
	v_mov_b32_dpp v32, v32 row_ror:1 row_mask:0xf bank_mask:0xf
	v_mov_b32_dpp v33, v31 row_ror:1 row_mask:0xf bank_mask:0xf
	v_mov_b32_dpp v31, v36 row_ror:15 row_mask:0xf bank_mask:0xf
	v_cndmask_b32_e64 v35, v27, v15, s[10:11]
	v_cndmask_b32_e64 v34, v26, v14, s[10:11]
	s_nop 1
	v_mov_b32_dpp v34, v34 row_ror:15 row_mask:0xf bank_mask:0xf
	v_mov_b32_dpp v35, v35 row_ror:15 row_mask:0xf bank_mask:0xf
	v_pk_fma_f32 v[28:29], v[88:89], v[28:29], v[92:93]
	v_pk_fma_f32 v[32:33], v[90:91], v[32:33], v[94:95]
	v_pk_fma_f32 v[28:29], v[24:25], v[84:85], v[28:29]
	v_cndmask_b32_e64 v23, v19, v23, s[12:13]
	v_pk_fma_f32 v[28:29], v[72:73], v[30:31], v[28:29]
	v_cndmask_b32_e64 v30, v18, v22, s[12:13]
	v_pk_fma_f32 v[32:33], v[26:27], v[86:87], v[32:33]
	s_nop 0
	v_mov_b32_dpp v30, v30 row_ror:1 row_mask:0xf bank_mask:0xf
	v_mov_b32_dpp v31, v23 row_ror:1 row_mask:0xf bank_mask:0xf
	v_pk_fma_f32 v[32:33], v[74:75], v[34:35], v[32:33]
	v_cndmask_b32_e64 v35, v19, v11, s[10:11]
	v_cndmask_b32_e64 v34, v18, v10, s[10:11]
	s_nop 1
	v_mov_b32_dpp v34, v34 row_ror:15 row_mask:0xf bank_mask:0xf
	v_mov_b32_dpp v35, v35 row_ror:15 row_mask:0xf bank_mask:0xf
	v_cndmask_b32_e64 v21, v17, v21, s[12:13]
	v_cndmask_b32_e64 v20, v16, v20, s[12:13]
	s_nop 1
	v_mov_b32_dpp v20, v20 row_ror:1 row_mask:0xf bank_mask:0xf
	v_mov_b32_dpp v21, v21 row_ror:1 row_mask:0xf bank_mask:0xf
	v_pk_fma_f32 v[30:31], v[78:79], v[30:31], v[82:83]
	v_cndmask_b32_e64 v36, v17, v9, s[10:11]
	v_cndmask_b32_e64 v22, v16, v8, s[10:11]
	v_pk_fma_f32 v[30:31], v[18:19], v[70:71], v[30:31]
	s_nop 0
	v_mov_b32_dpp v22, v22 row_ror:15 row_mask:0xf bank_mask:0xf
	v_mov_b32_dpp v23, v36 row_ror:15 row_mask:0xf bank_mask:0xf
	v_pk_fma_f32 v[30:31], v[66:67], v[34:35], v[30:31]
	v_mul_f32_e32 v34, 0xbfb8aa3b, v28
	v_mul_f32_e32 v35, 0xbfb8aa3b, v29
	v_exp_f32_e32 v34, v34
	v_exp_f32_e32 v35, v35
	v_pk_fma_f32 v[20:21], v[76:77], v[20:21], v[80:81]
	v_cndmask_b32_e64 v19, v11, v19, s[12:13]
	v_pk_fma_f32 v[20:21], v[16:17], v[68:69], v[20:21]
	v_cndmask_b32_e64 v17, v9, v17, s[12:13]
	v_pk_fma_f32 v[20:21], v[64:65], v[22:23], v[20:21]
	v_add_f32_e32 v22, 1.0, v34
	v_add_f32_e32 v23, 1.0, v35
	v_mul_f32_e32 v34, 0xbfb8aa3b, v32
	v_mul_f32_e32 v35, 0xbfb8aa3b, v33
	v_exp_f32_e32 v34, v34
	v_exp_f32_e32 v35, v35
	v_rcp_f32_e32 v22, v22
	v_rcp_f32_e32 v23, v23
	v_add_f32_e32 v34, 1.0, v34
	v_add_f32_e32 v35, 1.0, v35
	v_rcp_f32_e32 v34, v34
	v_rcp_f32_e32 v35, v35
	v_pk_mul_f32 v[22:23], v[28:29], v[22:23]
	v_cndmask_b32_e64 v29, v13, v5, s[10:11]
	v_pk_mul_f32 v[20:21], v[22:23], v[20:21]
	v_pk_mul_f32 v[22:23], v[32:33], v[34:35]
	v_cvt_pk_bf16_f32 v20, v20, v21
	v_pk_mul_f32 v[22:23], v[22:23], v[30:31]
	v_cndmask_b32_e64 v28, v14, v6, s[10:11]
	v_cvt_pk_bf16_f32 v21, v22, v23
; #define PG8_LAS __attribute__((address_space(3)))
; __device__ __forceinline__ unsigned pk2(float lo, float hi) { f32x2_pk v = {lo, hi}; bf16x2_pk b = __builtin_convertvector(v, bf16x2_pk); return __builtin_bit_cast(unsigned, b); }
; __device__ __forceinline__ float sigmoidf_(float x) { return __builtin_amdgcn_rcpf(1.0f + __expf(-x)); }
;     __device__ __forceinline__ void operator()(const f32x4 (&acc)[2][2][4][2], const Unit& u, int wr, int wc, int fr_, int fq_) const {
;     ...
;                 for (int m = 0; m < 4; ++m) { f32x4 cv[2];
; #pragma unroll
;                     for (int bj = 0; bj < 2; ++bj) {
;                         const f32x4 cur = acc[ai][bj][m][n];
;                         const f32x4 su = (fr == 15 && m > 0) ? acc[ai][bj][m > 0 ? m - 1 : 0][n] : cur;
;                         const f32x4 sd = (fr == 0 && m < 3) ? acc[ai][bj][m < 3 ? m + 1 : 3][n] : cur;
;                         f32x4 up, dn;
; #pragma unroll
;                         for (int e = 0; e < 4; ++e) { up[e] = __shfl(su[e], srcu); dn[e] = __shfl(sd[e], srcd); }
;                         if (m == 0) { f32x4 pv = (f32x4){0.f, 0.f, 0.f, 0.f}; if (sp >= 0) pv = *(const PG8_LAS f32x4*)(xch + sp * 256 + 128 * bj + cl + 4 * n); if (fr == 0) up = pv; }
;                         if (m == 3) { f32x4 nv = (f32x4){0.f, 0.f, 0.f, 0.f}; if (sn >= 0) nv = *(const PG8_LAS f32x4*)(xch + sn * 256 + 128 * bj + cl + 4 * n); if (fr == 15) dn = nv; }
;                         cv[bj] = bv[bj] + w0[bj] * up + w1[bj] * cur + w2[bj] * dn; }
;                     u32x2 hw; hw.x = pk2(cv[0][0] * sigmoidf_(cv[0][0]) * cv[1][0], cv[0][1] * sigmoidf_(cv[0][1]) * cv[1][1]); hw.y = pk2(cv[0][2] * sigmoidf_(cv[0][2]) * cv[1][2], cv[0][3] * sigmoidf_(cv[0][3]) * cv[1][3]);
;                     *(u32x2*)(H + (size_t)(u.pm * BM + ai * HALF + wr * 64 + m * 16 + fr) * 2816 + chg + 4 * n) = hw;
;                     asm volatile("" ::: "memory"); }
;             }
;         }
;         asm volatile("s_waitcnt lgkmcnt(0)" ::: "memory"); __builtin_amdgcn_s_barrier(); asm volatile("" ::: "memory");
	global_store_dwordx2 v[108:109], v[20:21], off offset:8
	v_cndmask_b32_e64 v21, v15, v27, s[12:13]
	v_cndmask_b32_e64 v23, v14, v26, s[12:13]
	v_cndmask_b32_e64 v26, v13, v25, s[12:13]
	v_cndmask_b32_e64 v20, v12, v24, s[12:13]
	s_nop 1
	v_mov_b32_dpp v20, v20 row_ror:1 row_mask:0xf bank_mask:0xf
	v_mov_b32_dpp v25, v21 row_ror:1 row_mask:0xf bank_mask:0xf
	v_mov_b32_dpp v21, v26 row_ror:1 row_mask:0xf bank_mask:0xf
	v_cndmask_b32_e64 v22, v12, v4, s[10:11]
	s_nop 1
	v_mov_b32_dpp v22, v22 row_ror:15 row_mask:0xf bank_mask:0xf
	v_mov_b32_dpp v24, v23 row_ror:1 row_mask:0xf bank_mask:0xf
	v_mov_b32_dpp v23, v29 row_ror:15 row_mask:0xf bank_mask:0xf
	v_cndmask_b32_e64 v27, v15, v7, s[10:11]
	v_mov_b32_dpp v26, v28 row_ror:15 row_mask:0xf bank_mask:0xf
	s_nop 0
	v_mov_b32_dpp v27, v27 row_ror:15 row_mask:0xf bank_mask:0xf
	v_pk_fma_f32 v[20:21], v[88:89], v[20:21], v[92:93]
	v_pk_fma_f32 v[24:25], v[90:91], v[24:25], v[94:95]
	v_pk_fma_f32 v[20:21], v[12:13], v[84:85], v[20:21]
	v_pk_fma_f32 v[24:25], v[14:15], v[86:87], v[24:25]
	v_pk_fma_f32 v[20:21], v[72:73], v[22:23], v[20:21]
	v_cndmask_b32_e64 v22, v10, v18, s[12:13]
	s_nop 1
	v_mov_b32_dpp v22, v22 row_ror:1 row_mask:0xf bank_mask:0xf
	v_mov_b32_dpp v23, v19 row_ror:1 row_mask:0xf bank_mask:0xf
	v_pk_fma_f32 v[24:25], v[74:75], v[26:27], v[24:25]
	v_cndmask_b32_e64 v27, v11, v3, s[10:11]
	v_cndmask_b32_e64 v26, v10, v2, s[10:11]
	s_nop 1
	v_mov_b32_dpp v26, v26 row_ror:15 row_mask:0xf bank_mask:0xf
	v_mov_b32_dpp v27, v27 row_ror:15 row_mask:0xf bank_mask:0xf
	v_cndmask_b32_e64 v16, v8, v16, s[12:13]
	s_nop 1
	v_mov_b32_dpp v16, v16 row_ror:1 row_mask:0xf bank_mask:0xf
	v_mov_b32_dpp v17, v17 row_ror:1 row_mask:0xf bank_mask:0xf
	v_pk_fma_f32 v[22:23], v[78:79], v[22:23], v[82:83]
	v_cndmask_b32_e64 v28, v9, v1, s[10:11]
	v_cndmask_b32_e64 v18, v8, v0, s[10:11]
	v_pk_fma_f32 v[22:23], v[10:11], v[70:71], v[22:23]
	s_nop 0
	v_mov_b32_dpp v18, v18 row_ror:15 row_mask:0xf bank_mask:0xf
	v_mov_b32_dpp v19, v28 row_ror:15 row_mask:0xf bank_mask:0xf
	v_pk_fma_f32 v[22:23], v[66:67], v[26:27], v[22:23]
	v_mul_f32_e32 v26, 0xbfb8aa3b, v20
	v_mul_f32_e32 v27, 0xbfb8aa3b, v21
	v_exp_f32_e32 v26, v26
	v_exp_f32_e32 v27, v27
	v_pk_fma_f32 v[16:17], v[76:77], v[16:17], v[80:81]
	v_cndmask_b32_e64 v15, v7, v15, s[12:13]
	v_pk_fma_f32 v[16:17], v[8:9], v[68:69], v[16:17]
	v_cndmask_b32_e64 v14, v6, v14, s[12:13]
	v_pk_fma_f32 v[16:17], v[64:65], v[18:19], v[16:17]
	v_add_f32_e32 v18, 1.0, v26
	v_add_f32_e32 v19, 1.0, v27
	v_mul_f32_e32 v26, 0xbfb8aa3b, v24
	v_mul_f32_e32 v27, 0xbfb8aa3b, v25
	v_exp_f32_e32 v26, v26
	v_exp_f32_e32 v27, v27
	v_rcp_f32_e32 v18, v18
	v_rcp_f32_e32 v19, v19
	v_add_f32_e32 v26, 1.0, v26
	v_add_f32_e32 v27, 1.0, v27
	v_rcp_f32_e32 v26, v26
	v_rcp_f32_e32 v27, v27
	v_pk_mul_f32 v[18:19], v[20:21], v[18:19]
	v_cndmask_b32_e64 v13, v5, v13, s[12:13]
	v_pk_mul_f32 v[16:17], v[18:19], v[16:17]
	v_pk_mul_f32 v[18:19], v[24:25], v[26:27]
	v_cndmask_b32_e64 v12, v4, v12, s[12:13]
	v_pk_mul_f32 v[18:19], v[18:19], v[22:23]
	v_cvt_pk_bf16_f32 v16, v16, v17
	v_cvt_pk_bf16_f32 v17, v18, v19
	v_mov_b32_dpp v20, v12 row_ror:1 row_mask:0xf bank_mask:0xf
	v_mov_b32_dpp v24, v4 row_ror:15 row_mask:0xf bank_mask:0xf
	v_mov_b32_dpp v21, v13 row_ror:1 row_mask:0xf bank_mask:0xf
	v_mov_b32_dpp v26, v5 row_ror:15 row_mask:0xf bank_mask:0xf
	v_mov_b32_dpp v22, v14 row_ror:1 row_mask:0xf bank_mask:0xf
	v_mov_b32_dpp v25, v6 row_ror:15 row_mask:0xf bank_mask:0xf
	v_mov_b32_dpp v23, v15 row_ror:1 row_mask:0xf bank_mask:0xf
	v_mov_b32_dpp v27, v7 row_ror:15 row_mask:0xf bank_mask:0xf
	global_store_dwordx2 v[110:111], v[16:17], off offset:8
	v_mov_b32_e32 v16, 0
	s_and_b64 vcc, exec, s[14:15]
	v_mov_b32_e32 v12, 0
	v_mov_b32_e32 v13, 0
	v_mov_b32_e32 v14, 0
	v_mov_b32_e32 v15, 0
	s_cbranch_vccnz .LBB0_1834
	ds_read_b128 v[12:15], v162 offset:16
.LBB0_1834:
	v_cndmask_b32_e64 v11, v3, v11, s[12:13]
	v_cndmask_b32_e64 v10, v2, v10, s[12:13]
	v_cndmask_b32_e64 v9, v1, v9, s[12:13]
	v_cndmask_b32_e64 v8, v0, v8, s[12:13]
	s_nop 1
	v_mov_b32_dpp v8, v8 row_ror:1 row_mask:0xf bank_mask:0xf
	v_mov_b32_dpp v28, v0 row_ror:15 row_mask:0xf bank_mask:0xf
	v_mov_b32_dpp v9, v9 row_ror:1 row_mask:0xf bank_mask:0xf
	v_mov_b32_dpp v30, v1 row_ror:15 row_mask:0xf bank_mask:0xf
	v_mov_b32_dpp v10, v10 row_ror:1 row_mask:0xf bank_mask:0xf
	v_mov_b32_dpp v29, v2 row_ror:15 row_mask:0xf bank_mask:0xf
	v_mov_b32_dpp v11, v11 row_ror:1 row_mask:0xf bank_mask:0xf
	v_mov_b32_dpp v31, v3 row_ror:15 row_mask:0xf bank_mask:0xf
	s_and_b64 vcc, exec, s[14:15]
	v_mov_b32_e32 v17, 0
	v_mov_b32_e32 v18, 0
	v_mov_b32_e32 v19, 0
	s_cbranch_vccnz .LBB0_1836
	ds_read_b128 v[16:19], v162 offset:528
.LBB0_1836:
	s_waitcnt lgkmcnt(0)
	v_pk_fma_f32 v[20:21], v[88:89], v[20:21], v[92:93]
	v_cndmask_b32_e64 v13, v26, v13, s[12:13]
	v_cndmask_b32_e64 v12, v24, v12, s[12:13]
	v_pk_fma_f32 v[22:23], v[90:91], v[22:23], v[94:95]
	v_pk_fma_f32 v[4:5], v[4:5], v[84:85], v[20:21]
	v_cndmask_b32_e64 v15, v27, v15, s[12:13]
	v_cndmask_b32_e64 v14, v25, v14, s[12:13]
	v_pk_fma_f32 v[6:7], v[6:7], v[86:87], v[22:23]
	v_pk_fma_f32 v[4:5], v[72:73], v[12:13], v[4:5]
	v_pk_fma_f32 v[8:9], v[76:77], v[8:9], v[80:81]
	v_pk_fma_f32 v[6:7], v[74:75], v[14:15], v[6:7]
	v_pk_fma_f32 v[10:11], v[78:79], v[10:11], v[82:83]
	v_pk_fma_f32 v[0:1], v[0:1], v[68:69], v[8:9]
	v_mul_f32_e32 v8, 0xbfb8aa3b, v4
	v_mul_f32_e32 v9, 0xbfb8aa3b, v5
	v_pk_fma_f32 v[2:3], v[2:3], v[70:71], v[10:11]
	v_exp_f32_e32 v8, v8
	v_exp_f32_e32 v9, v9
	v_mul_f32_e32 v10, 0xbfb8aa3b, v6
	v_mul_f32_e32 v11, 0xbfb8aa3b, v7
	v_exp_f32_e32 v10, v10
	v_exp_f32_e32 v11, v11
	v_add_f32_e32 v8, 1.0, v8
	v_add_f32_e32 v9, 1.0, v9
	v_rcp_f32_e32 v8, v8
	v_rcp_f32_e32 v9, v9
	v_add_f32_e32 v10, 1.0, v10
	v_add_f32_e32 v11, 1.0, v11
	v_rcp_f32_e32 v10, v10
	v_rcp_f32_e32 v11, v11
	v_cndmask_b32_e64 v17, v30, v17, s[12:13]
	v_cndmask_b32_e64 v16, v28, v16, s[12:13]
	v_cndmask_b32_e64 v19, v31, v19, s[12:13]
	v_cndmask_b32_e64 v18, v29, v18, s[12:13]
	v_pk_fma_f32 v[0:1], v[64:65], v[16:17], v[0:1]
	v_pk_mul_f32 v[4:5], v[4:5], v[8:9]
	v_pk_fma_f32 v[2:3], v[66:67], v[18:19], v[2:3]
	v_pk_mul_f32 v[0:1], v[4:5], v[0:1]
	v_pk_mul_f32 v[4:5], v[6:7], v[10:11]
	v_cvt_pk_bf16_f32 v0, v0, v1
	v_pk_mul_f32 v[2:3], v[4:5], v[2:3]
	s_andn2_b64 vcc, exec, s[6:7]
	v_cvt_pk_bf16_f32 v1, v2, v3
	global_store_dwordx2 v[114:115], v[0:1], off offset:8
	s_barrier
	s_mov_b64 s[6:7], -1
	s_cbranch_vccnz .LBB0_1796
	s_and_b64 vcc, exec, s[8:9]
	s_cbranch_vccnz .LBB0_1795
	s_barrier
	s_branch .LBB0_1795
